# v49 plus K-loops: first half-iteration of every unit peeled with SrcC = 0 on each accumulator's first MFMA; the 96/128 accumulator-zeroing v_mov per unit header deleted
# speedup vs baseline: 1.0034x; 1.0034x over previous
; #define PG8_STAGE(bufoff, gbase, voff) do { _Pragma("unroll") for (int _i = 0; _i < 2; ++_i) \
;         __builtin_amdgcn_global_load_lds((const unsigned*)((const char*)(gbase) + (voff)[_i]), (LAS unsigned*)(lds + (bufoff) + ldsw + _i * 8192), 16, 0, 0); } while (0)
; #define PG8_LDA(dst, b, h) do { _Pragma("unroll") for (int m = 0; m < NM; ++m) _Pragma("unroll") for (int k = 0; k < 2; ++k) dst[m][k] = *(const LAS bf16x8*)(lds + PG8_SA(b, h) + aoff + m * 2048 + k * 1024); } while (0)
; #define PG8_LDB(dst, b, h) do { _Pragma("unroll") for (int n = 0; n < 2; ++n) _Pragma("unroll") for (int k = 0; k < 2; ++k) dst[n][k] = *(const LAS bf16x8*)(lds + PG8_SB(b, h) + boff + n * 2048 + k * 1024); } while (0)
; #define PG8_MMA(ai, bj, At, Bt) do { __builtin_amdgcn_s_setprio(1); _Pragma("unroll") for (int m = 0; m < NM; ++m) _Pragma("unroll") for (int n = 0; n < 2; ++n) _Pragma("unroll") for (int k = 0; k < 2; ++k) \
;         acc[ai][bj][m][n] = __builtin_amdgcn_mfma_f32_16x16x32_bf16(Bt[n][k], At[m][k], acc[ai][bj][m][n], 0, 0, 0); __builtin_amdgcn_s_setprio(0); } while (0)
; #define PG8_WAIT_V(n) asm volatile("s_waitcnt vmcnt(" #n ")" ::: "memory")
; #define PG8_WAIT_L(n) asm volatile("s_waitcnt lgkmcnt(" #n ")" ::: "memory")
;     ...
;             const bool last = (t == nt - 2);
;             const char* a1 = cA + (size_t)(t + 1) * kstep;
;             const char* a2 = last ? nA : cA + (size_t)(t + 2) * kstep; const char* b2 = last ? nB : cB + (size_t)(t + 2) * kstep;
;             const char* a3 = a2 + kstep; const char* b3 = b2 + kstep;
;             if constexpr (SP2) {
;             PG8_LDB(B0, 0, 0); PG8_LDB(B1, 0, 1); PG8_SCHED; PG8_LDA(At, 0, 0); PG8_STAGE(PG8_SA(1, 1), a1 + hstepA, voffA);
;             PG8_WAIT_V(8); PG8_WAIT_L(0); PG8_BAR; PG8_MMA(0, 0, At, B0); PG8_MMA(0, 1, At, B1); PG8_BAR; PG8_SCHED;
;             PG8_LDA(At, 0, 1); PG8_STAGE(PG8_SB(0, 0), b2, voffB); PG8_STAGE(PG8_SB(0, 1), b2 + hstepB, voffB); PG8_STAGE(PG8_SA(0, 0), a2, voffA);
;             PG8_WAIT_V(8); PG8_WAIT_L(0); PG8_BAR; PG8_MMA(1, 0, At, B0); PG8_MMA(1, 1, At, B1); PG8_BAR; PG8_SCHED;
;     ...
; #pragma unroll
;         for (int a = 0; a < 2; ++a)
; #pragma unroll
;             for (int b = 0; b < 2; ++b)
; #pragma unroll
;                 for (int m = 0; m < NM; ++m)
; #pragma unroll
;                     for (int n = 0; n < 2; ++n) acc[a][b][m][n] = (f32x4){0.f, 0.f, 0.f, 0.f};
.LBB0_199:
	s_ashr_i32 s23, s22, 31
	s_lshl_b64 s[2:3], s[22:23], 20
	s_add_u32 s24, s33, s2
	s_addc_u32 s25, s36, s3
	s_and_b64 s[2:3], s[4:5], exec
	s_cselect_b32 s2, s25, s29
	s_cselect_b32 s3, s24, s28
	s_ashr_i32 s21, s20, 31
	s_lshl_b64 s[26:27], s[20:21], 20
	s_add_u32 s26, s37, s26
	s_addc_u32 s27, s38, s27
	s_and_b64 s[34:35], s[4:5], exec
	s_cselect_b32 s9, s27, s31
	s_cselect_b32 s21, s26, s30
	s_add_u32 s28, s28, 0x80080
	s_addc_u32 s29, s29, 0
	s_add_u32 s23, s30, 0x100
	s_addc_u32 s54, s31, 0
	s_mov_b32 s56, -2
	s_waitcnt vmcnt(5)
	ds_read_b128 v[26:29], v172
	ds_read_b128 v[30:33], v172 offset:1024
	ds_read_b128 v[42:45], v172 offset:2048
	ds_read_b128 v[46:49], v172 offset:3072
	ds_read_b128 v[146:149], v173
	ds_read_b128 v[150:153], v173 offset:1024
	ds_read_b128 v[164:167], v173 offset:2048
	ds_read_b128 v[168:171], v173 offset:3072
	s_add_u32 s30, s28, 0xfff80080
	s_addc_u32 s31, s29, -1
	s_cmp_eq_u32 s56, 28
	s_cselect_b32 s35, s2, s31
	s_cselect_b32 s34, s3, s30
	s_cselect_b32 s31, s9, s54
	s_cselect_b32 s30, s21, s23
	s_cselect_b32 s100, -1, 0
	s_andn2_b32 s100, s100, s101
	s_add_i32 m0, s43, 0xc000
	ds_read_b128 v[178:181], v174
	ds_read_b128 v[182:185], v174 offset:1024
	ds_read_b128 v[186:189], v174 offset:2048
	ds_read_b128 v[190:193], v174 offset:3072
	ds_read_b128 v[194:197], v174 offset:4096
	ds_read_b128 v[198:201], v174 offset:5120
	ds_read_b128 v[202:205], v174 offset:6144
	ds_read_b128 v[206:209], v174 offset:7168
	global_load_lds_dwordx4 v160, s[28:29]
	s_add_i32 m0, s43, 0xe000
	s_nop 0
	global_load_lds_dwordx4 v162, s[28:29]
	s_waitcnt vmcnt(8)
	s_waitcnt lgkmcnt(0)
	s_setprio 1
	s_barrier
	v_mfma_f32_16x16x32_bf16 v[142:145], v[26:29], v[178:181], 0
	v_mfma_f32_16x16x32_bf16 v[138:141], v[42:45], v[178:181], 0
	v_mfma_f32_16x16x32_bf16 v[126:129], v[26:29], v[186:189], 0
	v_mfma_f32_16x16x32_bf16 v[122:125], v[42:45], v[186:189], 0
	v_mfma_f32_16x16x32_bf16 v[110:113], v[26:29], v[194:197], 0
	v_mfma_f32_16x16x32_bf16 v[106:109], v[42:45], v[194:197], 0
	v_mfma_f32_16x16x32_bf16 v[94:97], v[26:29], v[202:205], 0
	v_mfma_f32_16x16x32_bf16 v[90:93], v[42:45], v[202:205], 0
	v_mfma_f32_16x16x32_bf16 v[142:145], v[30:33], v[182:185], v[142:145]
	v_mfma_f32_16x16x32_bf16 v[138:141], v[46:49], v[182:185], v[138:141]
	v_mfma_f32_16x16x32_bf16 v[126:129], v[30:33], v[190:193], v[126:129]
	v_mfma_f32_16x16x32_bf16 v[122:125], v[46:49], v[190:193], v[122:125]
	v_mfma_f32_16x16x32_bf16 v[110:113], v[30:33], v[198:201], v[110:113]
	v_mfma_f32_16x16x32_bf16 v[106:109], v[46:49], v[198:201], v[106:109]
	v_mfma_f32_16x16x32_bf16 v[94:97], v[30:33], v[206:209], v[94:97]
	v_mfma_f32_16x16x32_bf16 v[90:93], v[46:49], v[206:209], v[90:93]
	s_setprio 0
	s_setprio 1
	v_mfma_f32_16x16x32_bf16 v[134:137], v[146:149], v[178:181], 0
	v_mfma_f32_16x16x32_bf16 v[130:133], v[164:167], v[178:181], 0
	v_mfma_f32_16x16x32_bf16 v[118:121], v[146:149], v[186:189], 0
	v_mfma_f32_16x16x32_bf16 v[114:117], v[164:167], v[186:189], 0
	v_mfma_f32_16x16x32_bf16 v[102:105], v[146:149], v[194:197], 0
	v_mfma_f32_16x16x32_bf16 v[98:101], v[164:167], v[194:197], 0
	v_mfma_f32_16x16x32_bf16 v[86:89], v[146:149], v[202:205], 0
	v_mfma_f32_16x16x32_bf16 v[82:85], v[164:167], v[202:205], 0
	v_mfma_f32_16x16x32_bf16 v[134:137], v[150:153], v[182:185], v[134:137]
	v_mfma_f32_16x16x32_bf16 v[130:133], v[168:171], v[182:185], v[130:133]
	v_mfma_f32_16x16x32_bf16 v[118:121], v[150:153], v[190:193], v[118:121]
	v_mfma_f32_16x16x32_bf16 v[114:117], v[168:171], v[190:193], v[114:117]
	v_mfma_f32_16x16x32_bf16 v[102:105], v[150:153], v[198:201], v[102:105]
	v_mfma_f32_16x16x32_bf16 v[98:101], v[168:171], v[198:201], v[98:101]
	v_mfma_f32_16x16x32_bf16 v[86:89], v[150:153], v[206:209], v[86:89]
	v_mfma_f32_16x16x32_bf16 v[82:85], v[168:171], v[206:209], v[82:85]
	s_barrier
	s_setprio 0
	s_mov_b32 m0, s39
	v_lshl_add_u64 v[210:211], s[30:31], 0, v[0:1]
	s_add_u32 s72, s30, 0x80000
	s_addc_u32 s73, s31, 0
	ds_read_b128 v[178:181], v174 offset:16384
	ds_read_b128 v[182:185], v174 offset:17408
	ds_read_b128 v[186:189], v174 offset:18432
	ds_read_b128 v[190:193], v174 offset:19456
	ds_read_b128 v[194:197], v174 offset:20480
	ds_read_b128 v[198:201], v174 offset:21504
	ds_read_b128 v[202:205], v174 offset:22528
	ds_read_b128 v[206:209], v174 offset:23552
	s_cmp_lg_u32 s100, 0
	s_cbranch_scc1 .Ltl_ic_0s_p
	global_load_lds_dwordx4 v0, s[30:31]
	v_lshl_add_u64 v[212:213], s[30:31], 0, v[158:159]
	s_mov_b32 m0, s40
	s_nop 0
	global_load_lds_dwordx4 v158, s[30:31]
	s_mov_b32 m0, s41
	v_lshl_add_u64 v[216:217], s[34:35], 0, v[156:157]
	global_load_lds_dwordx4 v0, s[72:73]
	s_mov_b32 m0, s42
	s_nop 0
	global_load_lds_dwordx4 v158, s[72:73]
	v_lshl_add_u64 v[214:215], s[34:35], 0, v[154:155]
	s_mov_b32 m0, s43
	s_nop 0
	global_load_lds_dwordx4 v154, s[34:35]
	s_mov_b32 m0, s44
	s_nop 0
	global_load_lds_dwordx4 v156, s[34:35]
	s_waitcnt vmcnt(8)
	s_branch .Ltl_ic_0d_p

; #define PG8_MMA(ai, bj, At, Bt) do { __builtin_amdgcn_s_setprio(1); _Pragma("unroll") for (int m = 0; m < NM; ++m) _Pragma("unroll") for (int n = 0; n < 2; ++n) _Pragma("unroll") for (int k = 0; k < 2; ++k) \
;         acc[ai][bj][m][n] = __builtin_amdgcn_mfma_f32_16x16x32_bf16(Bt[n][k], At[m][k], acc[ai][bj][m][n], 0, 0, 0); __builtin_amdgcn_s_setprio(0); } while (0)
; #define PG8_WAIT_V(n) asm volatile("s_waitcnt vmcnt(" #n ")" ::: "memory")
; #define PG8_WAIT_L(n) asm volatile("s_waitcnt lgkmcnt(" #n ")" ::: "memory")
; #define PG8_BAR __builtin_amdgcn_s_barrier()
; #define PG8_SCHED __builtin_amdgcn_sched_barrier(0)
;     ...
;             PG8_WAIT_V(8); PG8_WAIT_L(0); PG8_BAR; PG8_MMA(1, 0, At, B0); PG8_MMA(1, 1, At, B1); PG8_BAR; PG8_SCHED;
.Ltl_ic_0d_p:
	s_waitcnt lgkmcnt(0)
	s_setprio 1
	s_barrier
	v_mfma_f32_16x16x32_bf16 v[78:81], v[26:29], v[178:181], 0
	v_mfma_f32_16x16x32_bf16 v[74:77], v[42:45], v[178:181], 0
	v_mfma_f32_16x16x32_bf16 v[62:65], v[26:29], v[186:189], 0
	v_mfma_f32_16x16x32_bf16 v[58:61], v[42:45], v[186:189], 0
	v_mfma_f32_16x16x32_bf16 v[38:41], v[26:29], v[194:197], 0
	v_mfma_f32_16x16x32_bf16 v[34:37], v[42:45], v[194:197], 0
	v_mfma_f32_16x16x32_bf16 v[14:17], v[26:29], v[202:205], 0
	v_mfma_f32_16x16x32_bf16 v[10:13], v[42:45], v[202:205], 0
	v_mfma_f32_16x16x32_bf16 v[78:81], v[30:33], v[182:185], v[78:81]
	v_mfma_f32_16x16x32_bf16 v[74:77], v[46:49], v[182:185], v[74:77]
	v_mfma_f32_16x16x32_bf16 v[62:65], v[30:33], v[190:193], v[62:65]
	v_mfma_f32_16x16x32_bf16 v[58:61], v[46:49], v[190:193], v[58:61]
	v_mfma_f32_16x16x32_bf16 v[38:41], v[30:33], v[198:201], v[38:41]
	v_mfma_f32_16x16x32_bf16 v[34:37], v[46:49], v[198:201], v[34:37]
	v_mfma_f32_16x16x32_bf16 v[14:17], v[30:33], v[206:209], v[14:17]
	v_mfma_f32_16x16x32_bf16 v[10:13], v[46:49], v[206:209], v[10:13]
	s_setprio 0
	s_setprio 1
	v_mfma_f32_16x16x32_bf16 v[22:25], v[146:149], v[194:197], 0
	v_mfma_f32_16x16x32_bf16 v[18:21], v[164:167], v[194:197], 0
	v_mfma_f32_16x16x32_bf16 v[6:9], v[146:149], v[202:205], 0
	v_mfma_f32_16x16x32_bf16 v[2:5], v[164:167], v[202:205], 0
	v_mfma_f32_16x16x32_bf16 v[26:29], v[146:149], v[178:181], 0
	v_mfma_f32_16x16x32_bf16 v[30:33], v[164:167], v[178:181], 0
	v_mfma_f32_16x16x32_bf16 v[42:45], v[146:149], v[186:189], 0
	v_mfma_f32_16x16x32_bf16 v[46:49], v[164:167], v[186:189], 0
	v_mfma_f32_16x16x32_bf16 v[22:25], v[150:153], v[198:201], v[22:25]
	v_mfma_f32_16x16x32_bf16 v[18:21], v[168:171], v[198:201], v[18:21]
	v_mfma_f32_16x16x32_bf16 v[6:9], v[150:153], v[206:209], v[6:9]
	v_mfma_f32_16x16x32_bf16 v[2:5], v[168:171], v[206:209], v[2:5]
	v_mfma_f32_16x16x32_bf16 v[26:29], v[150:153], v[182:185], v[26:29]
	v_mfma_f32_16x16x32_bf16 v[30:33], v[168:171], v[182:185], v[30:33]
	v_mfma_f32_16x16x32_bf16 v[42:45], v[150:153], v[190:193], v[42:45]
	v_mfma_f32_16x16x32_bf16 v[46:49], v[168:171], v[190:193], v[46:49]
	s_barrier
	s_branch .Lpeel_ic_mid

; #define PG8_STAGE(bufoff, gbase, voff) do { _Pragma("unroll") for (int _i = 0; _i < 2; ++_i) \
;         __builtin_amdgcn_global_load_lds((const unsigned*)((const char*)(gbase) + (voff)[_i]), (LAS unsigned*)(lds + (bufoff) + ldsw + _i * 8192), 16, 0, 0); } while (0)
; #define PG8_LDA(dst, b, h) do { _Pragma("unroll") for (int m = 0; m < NM; ++m) _Pragma("unroll") for (int k = 0; k < 2; ++k) dst[m][k] = *(const LAS bf16x8*)(lds + PG8_SA(b, h) + aoff + m * 2048 + k * 1024); } while (0)
; #define PG8_LDB(dst, b, h) do { _Pragma("unroll") for (int n = 0; n < 2; ++n) _Pragma("unroll") for (int k = 0; k < 2; ++k) dst[n][k] = *(const LAS bf16x8*)(lds + PG8_SB(b, h) + boff + n * 2048 + k * 1024); } while (0)
; #define PG8_MMA(ai, bj, At, Bt) do { __builtin_amdgcn_s_setprio(1); _Pragma("unroll") for (int m = 0; m < NM; ++m) _Pragma("unroll") for (int n = 0; n < 2; ++n) _Pragma("unroll") for (int k = 0; k < 2; ++k) \
;         acc[ai][bj][m][n] = __builtin_amdgcn_mfma_f32_16x16x32_bf16(Bt[n][k], At[m][k], acc[ai][bj][m][n], 0, 0, 0); __builtin_amdgcn_s_setprio(0); } while (0)
; #define PG8_WAIT_V(n) asm volatile("s_waitcnt vmcnt(" #n ")" ::: "memory")
; #define PG8_WAIT_L(n) asm volatile("s_waitcnt lgkmcnt(" #n ")" ::: "memory")
; #define PG8_BAR __builtin_amdgcn_s_barrier()
; #define PG8_SCHED __builtin_amdgcn_sched_barrier(0)
;     ...
;             PG8_LDB(B0, 1, 0); PG8_LDB(B1, 1, 1); PG8_SCHED; PG8_LDA(At, 1, 0); PG8_STAGE(PG8_SA(0, 1), a2 + hstepA, voffA);
;             PG8_WAIT_V(8); PG8_WAIT_L(0); PG8_BAR; PG8_MMA(0, 0, At, B0); PG8_MMA(0, 1, At, B1); PG8_BAR; PG8_SCHED;
.Lpeel_ic_mid:
	s_setprio 0
	ds_read_b128 v[50:53], v175
	ds_read_b128 v[54:57], v175 offset:1024
	ds_read_b128 v[66:69], v175 offset:2048
	ds_read_b128 v[70:73], v175 offset:3072
	ds_read_b128 v[146:149], v176
	ds_read_b128 v[150:153], v176 offset:1024
	ds_read_b128 v[164:167], v176 offset:2048
	ds_read_b128 v[168:171], v176 offset:3072
	s_add_u32 s34, s34, 0x80000
	s_addc_u32 s35, s35, 0
	s_mov_b32 m0, s45
	ds_read_b128 v[178:181], v174 offset:32768
	ds_read_b128 v[182:185], v174 offset:33792
	ds_read_b128 v[186:189], v174 offset:34816
	ds_read_b128 v[190:193], v174 offset:35840
	ds_read_b128 v[194:197], v174 offset:36864
	ds_read_b128 v[198:201], v174 offset:37888
	ds_read_b128 v[202:205], v174 offset:38912
	ds_read_b128 v[206:209], v174 offset:39936
	s_cmp_lg_u32 s100, 0
	s_cbranch_scc1 .Ltl_ic_1s
	global_load_lds_dwordx4 v154, s[34:35]
	s_mov_b32 m0, s46
	s_nop 0
	global_load_lds_dwordx4 v156, s[34:35]
	s_waitcnt vmcnt(8)
	s_branch .Ltl_ic_1d

; #define PG8_STAGE(bufoff, gbase, voff) do { _Pragma("unroll") for (int _i = 0; _i < 2; ++_i) \
;         __builtin_amdgcn_global_load_lds((const unsigned*)((const char*)(gbase) + (voff)[_i]), (LAS unsigned*)(lds + (bufoff) + ldsw + _i * 8192), 16, 0, 0); } while (0)
; #define PG8_LDA(dst, b, h) do { _Pragma("unroll") for (int m = 0; m < NM; ++m) _Pragma("unroll") for (int k = 0; k < 2; ++k) dst[m][k] = *(const LAS bf16x8*)(lds + PG8_SA(b, h) + aoff + m * 2048 + k * 1024); } while (0)
; #define PG8_LDB(dst, b, h) do { _Pragma("unroll") for (int n = 0; n < 2; ++n) _Pragma("unroll") for (int k = 0; k < 2; ++k) dst[n][k] = *(const LAS bf16x8*)(lds + PG8_SB(b, h) + boff + n * 2048 + k * 1024); } while (0)
; #define PG8_MMA(ai, bj, At, Bt) do { __builtin_amdgcn_s_setprio(1); _Pragma("unroll") for (int m = 0; m < NM; ++m) _Pragma("unroll") for (int n = 0; n < 2; ++n) _Pragma("unroll") for (int k = 0; k < 2; ++k) \
;         acc[ai][bj][m][n] = __builtin_amdgcn_mfma_f32_16x16x32_bf16(Bt[n][k], At[m][k], acc[ai][bj][m][n], 0, 0, 0); __builtin_amdgcn_s_setprio(0); } while (0)
; #define PG8_WAIT_V(n) asm volatile("s_waitcnt vmcnt(" #n ")" ::: "memory")
; #define PG8_WAIT_L(n) asm volatile("s_waitcnt lgkmcnt(" #n ")" ::: "memory")
;     ...
;             const bool last = (t == nt - 2);
;             const char* a1 = cA + (size_t)(t + 1) * kstep;
;             const char* a2 = last ? nA : cA + (size_t)(t + 2) * kstep; const char* b2 = last ? nB : cB + (size_t)(t + 2) * kstep;
;             const char* a3 = a2 + kstep; const char* b3 = b2 + kstep;
;             if constexpr (SP2) {
;             PG8_LDB(B0, 0, 0); PG8_LDB(B1, 0, 1); PG8_SCHED; PG8_LDA(At, 0, 0); PG8_STAGE(PG8_SA(1, 1), a1 + hstepA, voffA);
;             PG8_WAIT_V(8); PG8_WAIT_L(0); PG8_BAR; PG8_MMA(0, 0, At, B0); PG8_MMA(0, 1, At, B1); PG8_BAR; PG8_SCHED;
;             PG8_LDA(At, 0, 1); PG8_STAGE(PG8_SB(0, 0), b2, voffB); PG8_STAGE(PG8_SB(0, 1), b2 + hstepB, voffB); PG8_STAGE(PG8_SA(0, 0), a2, voffA);
;             PG8_WAIT_V(8); PG8_WAIT_L(0); PG8_BAR; PG8_MMA(1, 0, At, B0); PG8_MMA(1, 1, At, B1); PG8_BAR; PG8_SCHED;
;     ...
; #pragma unroll
;         for (int a = 0; a < 2; ++a)
; #pragma unroll
;             for (int b = 0; b < 2; ++b)
; #pragma unroll
;                 for (int m = 0; m < NM; ++m)
; #pragma unroll
;                     for (int n = 0; n < 2; ++n) acc[a][b][m][n] = (f32x4){0.f, 0.f, 0.f, 0.f};
.LBB0_702:
	s_ashr_i32 s29, s28, 31
	s_lshl_b64 s[2:3], s[28:29], 20
	s_add_u32 s30, s33, s2
	s_addc_u32 s31, s47, s3
	s_and_b64 s[2:3], s[4:5], exec
	s_cselect_b32 s2, s31, s11
	s_cselect_b32 s3, s30, s10
	s_ashr_i32 s27, s26, 31
	s_lshl_b64 s[34:35], s[26:27], 20
	s_add_u32 s34, s48, s34
	s_addc_u32 s35, s49, s35
	s_and_b64 s[36:37], s[4:5], exec
	s_cselect_b32 s9, s35, s13
	s_cselect_b32 s27, s34, s12
	s_add_u32 s10, s10, 0x80080
	s_addc_u32 s11, s11, 0
	s_add_u32 s29, s12, 0x100
	s_addc_u32 s38, s13, 0
	s_mov_b32 s39, -2
	v_add_u32_e32 v0, s50, v146
	ds_read_b128 v[138:141], v0
	ds_read_b128 v[142:145], v0 offset:1024
	ds_read_b128 v[148:151], v0 offset:2048
	ds_read_b128 v[152:155], v0 offset:3072
	v_add_u32_e32 v0, s54, v146
	ds_read_b128 v[156:159], v0
	ds_read_b128 v[160:163], v0 offset:1024
	ds_read_b128 v[164:167], v0 offset:2048
	ds_read_b128 v[168:171], v0 offset:3072
	s_add_u32 s12, s10, 0xfff80080
	s_addc_u32 s13, s11, -1
	s_cmp_eq_u32 s39, 28
	s_cselect_b32 s37, s2, s13
	s_cselect_b32 s36, s3, s12
	s_cselect_b32 s13, s9, s38
	s_cselect_b32 s12, s27, s29
	s_cselect_b32 s100, -1, 0
	s_andn2_b32 s100, s100, s101
	s_add_i32 m0, s58, 0xc000
	ds_read_b128 v[172:175], v147
	ds_read_b128 v[176:179], v147 offset:1024
	ds_read_b128 v[180:183], v147 offset:2048
	ds_read_b128 v[184:187], v147 offset:3072
	ds_read_b128 v[188:191], v147 offset:4096
	ds_read_b128 v[192:195], v147 offset:5120
	ds_read_b128 v[196:199], v147 offset:6144
	ds_read_b128 v[200:203], v147 offset:7168
	global_load_lds_dwordx4 v134, s[10:11]
	s_add_i32 m0, s58, 0xe000
	s_nop 0
	global_load_lds_dwordx4 v136, s[10:11]
	s_waitcnt vmcnt(8)
	s_waitcnt lgkmcnt(0)
	s_setprio 1
	s_barrier
	v_mfma_f32_16x16x32_bf16 v[126:129], v[138:141], v[172:175], 0
	v_mfma_f32_16x16x32_bf16 v[122:125], v[148:151], v[172:175], 0
	v_mfma_f32_16x16x32_bf16 v[110:113], v[138:141], v[180:183], 0
	v_mfma_f32_16x16x32_bf16 v[106:109], v[148:151], v[180:183], 0
	v_mfma_f32_16x16x32_bf16 v[94:97], v[138:141], v[188:191], 0
	v_mfma_f32_16x16x32_bf16 v[90:93], v[148:151], v[188:191], 0
	v_mfma_f32_16x16x32_bf16 v[78:81], v[138:141], v[196:199], 0
	v_mfma_f32_16x16x32_bf16 v[74:77], v[148:151], v[196:199], 0
	v_mfma_f32_16x16x32_bf16 v[126:129], v[142:145], v[176:179], v[126:129]
	v_mfma_f32_16x16x32_bf16 v[122:125], v[152:155], v[176:179], v[122:125]
	v_mfma_f32_16x16x32_bf16 v[110:113], v[142:145], v[184:187], v[110:113]
	v_mfma_f32_16x16x32_bf16 v[106:109], v[152:155], v[184:187], v[106:109]
	v_mfma_f32_16x16x32_bf16 v[94:97], v[142:145], v[192:195], v[94:97]
	v_mfma_f32_16x16x32_bf16 v[90:93], v[152:155], v[192:195], v[90:93]
	v_mfma_f32_16x16x32_bf16 v[78:81], v[142:145], v[200:203], v[78:81]
	v_mfma_f32_16x16x32_bf16 v[74:77], v[152:155], v[200:203], v[74:77]
	s_setprio 0
	s_setprio 1
	v_mfma_f32_16x16x32_bf16 v[118:121], v[156:159], v[172:175], 0
	v_mfma_f32_16x16x32_bf16 v[114:117], v[164:167], v[172:175], 0
	v_mfma_f32_16x16x32_bf16 v[102:105], v[156:159], v[180:183], 0
	v_mfma_f32_16x16x32_bf16 v[98:101], v[164:167], v[180:183], 0
	v_mfma_f32_16x16x32_bf16 v[86:89], v[156:159], v[188:191], 0
	v_mfma_f32_16x16x32_bf16 v[82:85], v[164:167], v[188:191], 0
	v_mfma_f32_16x16x32_bf16 v[70:73], v[156:159], v[196:199], 0
	v_mfma_f32_16x16x32_bf16 v[66:69], v[164:167], v[196:199], 0
	v_mfma_f32_16x16x32_bf16 v[118:121], v[160:163], v[176:179], v[118:121]
	v_mfma_f32_16x16x32_bf16 v[114:117], v[168:171], v[176:179], v[114:117]
	v_mfma_f32_16x16x32_bf16 v[102:105], v[160:163], v[184:187], v[102:105]
	v_mfma_f32_16x16x32_bf16 v[98:101], v[168:171], v[184:187], v[98:101]
	v_mfma_f32_16x16x32_bf16 v[86:89], v[160:163], v[192:195], v[86:89]
	v_mfma_f32_16x16x32_bf16 v[82:85], v[168:171], v[192:195], v[82:85]
	v_mfma_f32_16x16x32_bf16 v[70:73], v[160:163], v[200:203], v[70:73]
	v_mfma_f32_16x16x32_bf16 v[66:69], v[168:171], v[200:203], v[66:69]
	s_barrier
	s_setprio 0
	s_mov_b32 m0, s51
	v_lshl_add_u64 v[204:205], s[12:13], 0, v[130:131]
	s_add_u32 s40, s12, 0x80000
	s_addc_u32 s41, s13, 0
	ds_read_b128 v[172:175], v147 offset:16384
	ds_read_b128 v[176:179], v147 offset:17408
	ds_read_b128 v[180:183], v147 offset:18432
	ds_read_b128 v[184:187], v147 offset:19456
	ds_read_b128 v[188:191], v147 offset:20480
	ds_read_b128 v[192:195], v147 offset:21504
	ds_read_b128 v[196:199], v147 offset:22528
	ds_read_b128 v[200:203], v147 offset:23552
	s_cmp_lg_u32 s100, 0
	s_cbranch_scc1 .Ltl_ia_0s_p
	global_load_lds_dwordx4 v130, s[12:13]
	v_lshl_add_u64 v[206:207], s[12:13], 0, v[132:133]
	s_mov_b32 m0, s52
	s_nop 0
	global_load_lds_dwordx4 v132, s[12:13]
	s_mov_b32 m0, s56
	v_lshl_add_u64 v[210:211], s[36:37], 0, v[132:133]
	global_load_lds_dwordx4 v130, s[40:41]
	s_mov_b32 m0, s57
	s_nop 0
	global_load_lds_dwordx4 v132, s[40:41]
	v_lshl_add_u64 v[208:209], s[36:37], 0, v[130:131]
	s_mov_b32 m0, s58
	s_nop 0
	global_load_lds_dwordx4 v130, s[36:37]
	s_mov_b32 m0, s59
	s_nop 0
	global_load_lds_dwordx4 v132, s[36:37]
	s_waitcnt vmcnt(8)
	s_branch .Ltl_ia_0d_p

; #define PG8_MMA(ai, bj, At, Bt) do { __builtin_amdgcn_s_setprio(1); _Pragma("unroll") for (int m = 0; m < NM; ++m) _Pragma("unroll") for (int n = 0; n < 2; ++n) _Pragma("unroll") for (int k = 0; k < 2; ++k) \
;         acc[ai][bj][m][n] = __builtin_amdgcn_mfma_f32_16x16x32_bf16(Bt[n][k], At[m][k], acc[ai][bj][m][n], 0, 0, 0); __builtin_amdgcn_s_setprio(0); } while (0)
; #define PG8_WAIT_V(n) asm volatile("s_waitcnt vmcnt(" #n ")" ::: "memory")
; #define PG8_WAIT_L(n) asm volatile("s_waitcnt lgkmcnt(" #n ")" ::: "memory")
; #define PG8_BAR __builtin_amdgcn_s_barrier()
; #define PG8_SCHED __builtin_amdgcn_sched_barrier(0)
;     ...
;             PG8_WAIT_V(8); PG8_WAIT_L(0); PG8_BAR; PG8_MMA(1, 0, At, B0); PG8_MMA(1, 1, At, B1); PG8_BAR; PG8_SCHED;
.Ltl_ia_0d_p:
	s_waitcnt lgkmcnt(0)
	s_setprio 1
	s_barrier
	v_mfma_f32_16x16x32_bf16 v[62:65], v[138:141], v[172:175], 0
	v_mfma_f32_16x16x32_bf16 v[58:61], v[148:151], v[172:175], 0
	v_mfma_f32_16x16x32_bf16 v[46:49], v[138:141], v[180:183], 0
	v_mfma_f32_16x16x32_bf16 v[42:45], v[148:151], v[180:183], 0
	v_mfma_f32_16x16x32_bf16 v[30:33], v[138:141], v[188:191], 0
	v_mfma_f32_16x16x32_bf16 v[26:29], v[148:151], v[188:191], 0
	v_mfma_f32_16x16x32_bf16 v[14:17], v[138:141], v[196:199], 0
	v_mfma_f32_16x16x32_bf16 v[10:13], v[148:151], v[196:199], 0
	v_mfma_f32_16x16x32_bf16 v[62:65], v[142:145], v[176:179], v[62:65]
	v_mfma_f32_16x16x32_bf16 v[58:61], v[152:155], v[176:179], v[58:61]
	v_mfma_f32_16x16x32_bf16 v[46:49], v[142:145], v[184:187], v[46:49]
	v_mfma_f32_16x16x32_bf16 v[42:45], v[152:155], v[184:187], v[42:45]
	v_mfma_f32_16x16x32_bf16 v[30:33], v[142:145], v[192:195], v[30:33]
	v_mfma_f32_16x16x32_bf16 v[26:29], v[152:155], v[192:195], v[26:29]
	v_mfma_f32_16x16x32_bf16 v[14:17], v[142:145], v[200:203], v[14:17]
	v_mfma_f32_16x16x32_bf16 v[10:13], v[152:155], v[200:203], v[10:13]
	s_setprio 0
	s_setprio 1
	v_mfma_f32_16x16x32_bf16 v[54:57], v[156:159], v[172:175], 0
	v_mfma_f32_16x16x32_bf16 v[50:53], v[164:167], v[172:175], 0
	v_mfma_f32_16x16x32_bf16 v[38:41], v[156:159], v[180:183], 0
	v_mfma_f32_16x16x32_bf16 v[34:37], v[164:167], v[180:183], 0
	v_mfma_f32_16x16x32_bf16 v[22:25], v[156:159], v[188:191], 0
	v_mfma_f32_16x16x32_bf16 v[18:21], v[164:167], v[188:191], 0
	v_mfma_f32_16x16x32_bf16 v[6:9], v[156:159], v[196:199], 0
	v_mfma_f32_16x16x32_bf16 v[2:5], v[164:167], v[196:199], 0
	v_mfma_f32_16x16x32_bf16 v[54:57], v[160:163], v[176:179], v[54:57]
	v_mfma_f32_16x16x32_bf16 v[50:53], v[168:171], v[176:179], v[50:53]
	v_mfma_f32_16x16x32_bf16 v[38:41], v[160:163], v[184:187], v[38:41]
	v_mfma_f32_16x16x32_bf16 v[34:37], v[168:171], v[184:187], v[34:37]
	v_mfma_f32_16x16x32_bf16 v[22:25], v[160:163], v[192:195], v[22:25]
	v_mfma_f32_16x16x32_bf16 v[18:21], v[168:171], v[192:195], v[18:21]
	v_mfma_f32_16x16x32_bf16 v[6:9], v[160:163], v[200:203], v[6:9]
	v_mfma_f32_16x16x32_bf16 v[2:5], v[168:171], v[200:203], v[2:5]
	s_barrier
	s_branch .Lpeel_ia_mid

; #define PG8_STAGE(bufoff, gbase, voff) do { _Pragma("unroll") for (int _i = 0; _i < 2; ++_i) \
;         __builtin_amdgcn_global_load_lds((const unsigned*)((const char*)(gbase) + (voff)[_i]), (LAS unsigned*)(lds + (bufoff) + ldsw + _i * 8192), 16, 0, 0); } while (0)
; #define PG8_LDA(dst, b, h) do { _Pragma("unroll") for (int m = 0; m < NM; ++m) _Pragma("unroll") for (int k = 0; k < 2; ++k) dst[m][k] = *(const LAS bf16x8*)(lds + PG8_SA(b, h) + aoff + m * 2048 + k * 1024); } while (0)
; #define PG8_LDB(dst, b, h) do { _Pragma("unroll") for (int n = 0; n < 2; ++n) _Pragma("unroll") for (int k = 0; k < 2; ++k) dst[n][k] = *(const LAS bf16x8*)(lds + PG8_SB(b, h) + boff + n * 2048 + k * 1024); } while (0)
; #define PG8_MMA(ai, bj, At, Bt) do { __builtin_amdgcn_s_setprio(1); _Pragma("unroll") for (int m = 0; m < NM; ++m) _Pragma("unroll") for (int n = 0; n < 2; ++n) _Pragma("unroll") for (int k = 0; k < 2; ++k) \
;         acc[ai][bj][m][n] = __builtin_amdgcn_mfma_f32_16x16x32_bf16(Bt[n][k], At[m][k], acc[ai][bj][m][n], 0, 0, 0); __builtin_amdgcn_s_setprio(0); } while (0)
; #define PG8_WAIT_V(n) asm volatile("s_waitcnt vmcnt(" #n ")" ::: "memory")
; #define PG8_WAIT_L(n) asm volatile("s_waitcnt lgkmcnt(" #n ")" ::: "memory")
; #define PG8_BAR __builtin_amdgcn_s_barrier()
; #define PG8_SCHED __builtin_amdgcn_sched_barrier(0)
;     ...
;             PG8_LDB(B0, 1, 0); PG8_LDB(B1, 1, 1); PG8_SCHED; PG8_LDA(At, 1, 0); PG8_STAGE(PG8_SA(0, 1), a2 + hstepA, voffA);
;             PG8_WAIT_V(8); PG8_WAIT_L(0); PG8_BAR; PG8_MMA(0, 0, At, B0); PG8_MMA(0, 1, At, B1); PG8_BAR; PG8_SCHED;
.Lpeel_ia_mid:
	s_setprio 0
	v_add_u32_e32 v0, s64, v146
	ds_read_b128 v[138:141], v0
	ds_read_b128 v[142:145], v0 offset:1024
	ds_read_b128 v[148:151], v0 offset:2048
	ds_read_b128 v[152:155], v0 offset:3072
	v_add_u32_e32 v0, s71, v146
	ds_read_b128 v[156:159], v0
	ds_read_b128 v[160:163], v0 offset:1024
	ds_read_b128 v[164:167], v0 offset:2048
	ds_read_b128 v[168:171], v0 offset:3072
	s_add_u32 s36, s36, 0x80000
	s_addc_u32 s37, s37, 0
	s_mov_b32 m0, s62
	ds_read_b128 v[172:175], v147 offset:32768
	ds_read_b128 v[176:179], v147 offset:33792
	ds_read_b128 v[180:183], v147 offset:34816
	ds_read_b128 v[184:187], v147 offset:35840
	ds_read_b128 v[188:191], v147 offset:36864
	ds_read_b128 v[192:195], v147 offset:37888
	ds_read_b128 v[196:199], v147 offset:38912
	ds_read_b128 v[200:203], v147 offset:39936
	s_cmp_lg_u32 s100, 0
	s_cbranch_scc1 .Ltl_ia_1s
	global_load_lds_dwordx4 v130, s[36:37]
	s_mov_b32 m0, s63
	s_nop 0
	global_load_lds_dwordx4 v132, s[36:37]
	s_waitcnt vmcnt(8)
	s_branch .Ltl_ia_1d

; #define LAS __attribute__((address_space(3)))
; __device__ __forceinline__ int lane_id() { int l; asm volatile("v_mbcnt_lo_u32_b32 %0, -1, 0\n\tv_mbcnt_hi_u32_b32 %0, -1, %0" : "=v"(l)); return l; }
;     __device__ __forceinline__ size_t aoff(const Unit& u) const { return (size_t)u.pm * bm * lda * 2; }
;     __device__ __forceinline__ size_t boff(const Unit& u) const { return (size_t)u.pn * BM * ldb * 2; }
;     __device__ __forceinline__ size_t aoff(const Unit& u) const { return ((size_t)u.pm * BM * lda + (size_t)u.pn * akoff) * 2; }
;     __device__ __forceinline__ size_t boff(const Unit& u) const { return (size_t)u.pn * BM * ldb * 2; }
;     __device__ __forceinline__ size_t aoff(const Unit& u) const { return ((size_t)u.pm * BM * lda + (size_t)(u.pn >> 1) * akoff) * 2; }
; #define PG8_WAIT_V(n) asm volatile("s_waitcnt vmcnt(" #n ")" ::: "memory")
;     ...
;         const bool has_next = S.next(ui + 1, nxt);
;         const char* nA = has_next ? (const char*)g.A + S.aoff(nxt) : cA; const char* nB = has_next ? (const char*)g.Bt + S.boff(nxt) : cB;
;         if constexpr (Epi::PRE) E.pre(lds, cur, wid);
;         for (int t = 0; t < nt; t += 2) {
;             const bool last = (t == nt - 2);
;             const char* a1 = cA + (size_t)(t + 1) * kstep;
;             const char* a2 = last ? nA : cA + (size_t)(t + 2) * kstep; const char* b2 = last ? nB : cB + (size_t)(t + 2) * kstep;
;             const char* a3 = a2 + kstep; const char* b3 = b2 + kstep;
;             if constexpr (SP2) {
;             PG8_LDB(B0, 0, 0); PG8_LDB(B1, 0, 1); PG8_SCHED; PG8_LDA(At, 0, 0); PG8_STAGE(PG8_SA(1, 1), a1 + hstepA, voffA);
;             PG8_WAIT_V(8); PG8_WAIT_L(0); PG8_BAR; PG8_MMA(0, 0, At, B0); PG8_MMA(0, 1, At, B1); PG8_BAR; PG8_SCHED;
;             PG8_LDA(At, 0, 1); PG8_STAGE(PG8_SB(0, 0), b2, voffB); PG8_STAGE(PG8_SB(0, 1), b2 + hstepB, voffB); PG8_STAGE(PG8_SA(0, 0), a2, voffA);
;             PG8_WAIT_V(8); PG8_WAIT_L(0); PG8_BAR; PG8_MMA(1, 0, At, B0); PG8_MMA(1, 1, At, B1); PG8_BAR; PG8_SCHED;
;     __device__ __forceinline__ void pre(LAS unsigned char* l, const pg8::Unit& u, int wid) const {
;         const float* src = (const float*)(ws + WS_SSQQ) + ((size_t)li * 8 + wid) * MT + u.pm * 256 + lane_id() * 4;
;         __builtin_amdgcn_global_load_lds((const unsigned*)src, (LAS unsigned*)(l + EPI_LDS + u.par * 8192 + wid * 1024), 16, 0, 0);
;     }
.LBB0_1191:
	s_ashr_i32 s27, s26, 31
	s_lshl_b64 s[2:3], s[26:27], 18
	s_add_u32 s28, s33, s2
	s_addc_u32 s29, s43, s3
	s_and_b64 s[2:3], s[4:5], exec
	s_cselect_b32 s2, s29, s11
	s_cselect_b32 s3, s28, s10
	s_ashr_i32 s25, s24, 31
	s_lshl_b64 s[30:31], s[24:25], 18
	s_add_u32 s30, s44, s30
	s_addc_u32 s31, s45, s31
	s_and_b64 s[56:57], s[4:5], exec
	s_cselect_b32 s7, s31, s13
	s_cselect_b32 s27, s30, s12
	s_lshl_b32 s8, s8, 8
	s_ashr_i32 s9, s8, 31
	s_lshl_b64 s[56:57], s[8:9], 2
	s_add_u32 s56, s94, s56
	v_mbcnt_lo_u32_b32 v0, -1, 0
	v_mbcnt_hi_u32_b32 v0, -1, v0
	s_addc_u32 s57, s95, s57
	v_lshlrev_b32_e32 v2, 2, v0
	v_ashrrev_i32_e32 v3, 31, v2
	s_lshl_b32 s25, s34, 13
	v_lshl_add_u64 v[2:3], v[2:3], 2, s[56:57]
	s_add_i32 m0, s81, s25
	s_add_u32 s10, s10, 0x20080
	global_load_lds_dwordx4 v[2:3], off
	s_addc_u32 s11, s11, 0
	s_add_u32 s9, s12, 0x100
	s_addc_u32 s52, s13, 0
	s_mov_b32 s54, -2
	v_add_u32_e32 v0, s49, v216
	ds_read_b128 v[10:13], v0
	ds_read_b128 v[14:17], v0 offset:1024
	ds_read_b128 v[18:21], v0 offset:2048
	ds_read_b128 v[22:25], v0 offset:3072
	v_add_u32_e32 v0, s58, v216
	ds_read_b128 v[26:29], v0
	ds_read_b128 v[30:33], v0 offset:1024
	ds_read_b128 v[42:45], v0 offset:2048
	ds_read_b128 v[46:49], v0 offset:3072
	s_add_u32 s12, s10, 0xfffe0080
	s_addc_u32 s13, s11, -1
	s_cmp_eq_u32 s54, 4
	s_cselect_b32 s35, s2, s13
	s_cselect_b32 s34, s3, s12
	s_cselect_b32 s13, s7, s52
	s_cselect_b32 s12, s27, s9
	s_cselect_b32 s100, -1, 0
	s_andn2_b32 s100, s100, s101
	s_add_i32 m0, s62, 0xc000
	ds_read_b128 v[50:53], v217
	ds_read_b128 v[54:57], v217 offset:1024
	ds_read_b128 v[58:61], v217 offset:2048
	ds_read_b128 v[62:65], v217 offset:3072
	ds_read_b128 v[178:181], v217 offset:4096
	ds_read_b128 v[182:185], v217 offset:5120
	ds_read_b128 v[198:201], v217 offset:6144
	ds_read_b128 v[208:211], v217 offset:7168
	global_load_lds_dwordx4 v194, s[10:11]
	s_add_i32 m0, s62, 0xe000
	s_nop 0
	global_load_lds_dwordx4 v196, s[10:11]
	s_waitcnt vmcnt(8)
	s_waitcnt lgkmcnt(0)
	s_setprio 1
	s_barrier
	v_mfma_f32_16x16x32_bf16 v[38:41], v[10:13], v[50:53], 0
	v_mfma_f32_16x16x32_bf16 v[34:37], v[18:21], v[50:53], 0
	v_mfma_f32_16x16x32_bf16 v[174:177], v[10:13], v[58:61], 0
	v_mfma_f32_16x16x32_bf16 v[170:173], v[18:21], v[58:61], 0
	v_mfma_f32_16x16x32_bf16 v[158:161], v[10:13], v[178:181], 0
	v_mfma_f32_16x16x32_bf16 v[154:157], v[18:21], v[178:181], 0
	v_mfma_f32_16x16x32_bf16 v[142:145], v[10:13], v[198:201], 0
	v_mfma_f32_16x16x32_bf16 v[138:141], v[18:21], v[198:201], 0
	v_mfma_f32_16x16x32_bf16 v[38:41], v[14:17], v[54:57], v[38:41]
	v_mfma_f32_16x16x32_bf16 v[34:37], v[22:25], v[54:57], v[34:37]
	v_mfma_f32_16x16x32_bf16 v[174:177], v[14:17], v[62:65], v[174:177]
	v_mfma_f32_16x16x32_bf16 v[170:173], v[22:25], v[62:65], v[170:173]
	v_mfma_f32_16x16x32_bf16 v[158:161], v[14:17], v[182:185], v[158:161]
	v_mfma_f32_16x16x32_bf16 v[154:157], v[22:25], v[182:185], v[154:157]
	v_mfma_f32_16x16x32_bf16 v[142:145], v[14:17], v[208:211], v[142:145]
	v_mfma_f32_16x16x32_bf16 v[138:141], v[22:25], v[208:211], v[138:141]
	s_setprio 0
	s_setprio 1
	v_mfma_f32_16x16x32_bf16 v[6:9], v[26:29], v[50:53], 0
	v_mfma_f32_16x16x32_bf16 v[2:5], v[42:45], v[50:53], 0
	v_mfma_f32_16x16x32_bf16 v[6:9], v[30:33], v[54:57], v[6:9]
	v_mfma_f32_16x16x32_bf16 v[2:5], v[46:49], v[54:57], v[2:5]
	v_mfma_f32_16x16x32_bf16 v[50:53], v[26:29], v[58:61], 0
	v_mfma_f32_16x16x32_bf16 v[54:57], v[42:45], v[58:61], 0
	v_mfma_f32_16x16x32_bf16 v[134:137], v[26:29], v[198:201], 0
	v_mfma_f32_16x16x32_bf16 v[130:133], v[42:45], v[198:201], 0
	v_mfma_f32_16x16x32_bf16 v[50:53], v[30:33], v[62:65], v[50:53]
	v_mfma_f32_16x16x32_bf16 v[54:57], v[46:49], v[62:65], v[54:57]
	v_mfma_f32_16x16x32_bf16 v[58:61], v[26:29], v[178:181], 0
	v_mfma_f32_16x16x32_bf16 v[62:65], v[42:45], v[178:181], 0
	v_mfma_f32_16x16x32_bf16 v[134:137], v[30:33], v[208:211], v[134:137]
	v_mfma_f32_16x16x32_bf16 v[130:133], v[46:49], v[208:211], v[130:133]
	v_mfma_f32_16x16x32_bf16 v[58:61], v[30:33], v[182:185], v[58:61]
	v_mfma_f32_16x16x32_bf16 v[62:65], v[46:49], v[182:185], v[62:65]
	s_barrier
	s_setprio 0
	s_mov_b32 m0, s50
	v_lshl_add_u64 v[202:203], s[12:13], 0, v[188:189]
	s_add_u32 s56, s12, 0x20000
	s_addc_u32 s57, s13, 0
	ds_read_b128 v[146:149], v217 offset:16384
	ds_read_b128 v[150:153], v217 offset:17408
	ds_read_b128 v[162:165], v217 offset:18432
	ds_read_b128 v[166:169], v217 offset:19456
	ds_read_b128 v[178:181], v217 offset:20480
	ds_read_b128 v[182:185], v217 offset:21504
	ds_read_b128 v[198:201], v217 offset:22528
	ds_read_b128 v[208:211], v217 offset:23552
	s_cmp_lg_u32 s100, 0
	s_cbranch_scc1 .Ltl_qp_0s_p
	global_load_lds_dwordx4 v188, s[12:13]
	v_lshl_add_u64 v[204:205], s[12:13], 0, v[192:193]
	s_mov_b32 m0, s51
	s_nop 0
	global_load_lds_dwordx4 v192, s[12:13]
	s_mov_b32 m0, s59
	v_lshl_add_u64 v[222:223], s[34:35], 0, v[190:191]
	global_load_lds_dwordx4 v188, s[56:57]
	s_mov_b32 m0, s60
	s_nop 0
	global_load_lds_dwordx4 v192, s[56:57]
	v_lshl_add_u64 v[206:207], s[34:35], 0, v[186:187]
	s_mov_b32 m0, s62
	s_nop 0
	global_load_lds_dwordx4 v186, s[34:35]
	s_mov_b32 m0, s63
	s_nop 0
	global_load_lds_dwordx4 v190, s[34:35]
	s_waitcnt vmcnt(8)
	s_branch .Ltl_qp_0d_p

; #define PG8_MMA(ai, bj, At, Bt) do { __builtin_amdgcn_s_setprio(1); _Pragma("unroll") for (int m = 0; m < NM; ++m) _Pragma("unroll") for (int n = 0; n < 2; ++n) _Pragma("unroll") for (int k = 0; k < 2; ++k) \
;         acc[ai][bj][m][n] = __builtin_amdgcn_mfma_f32_16x16x32_bf16(Bt[n][k], At[m][k], acc[ai][bj][m][n], 0, 0, 0); __builtin_amdgcn_s_setprio(0); } while (0)
; #define PG8_WAIT_V(n) asm volatile("s_waitcnt vmcnt(" #n ")" ::: "memory")
; #define PG8_WAIT_L(n) asm volatile("s_waitcnt lgkmcnt(" #n ")" ::: "memory")
; #define PG8_BAR __builtin_amdgcn_s_barrier()
; #define PG8_SCHED __builtin_amdgcn_sched_barrier(0)
;     ...
;             PG8_WAIT_V(8); PG8_WAIT_L(0); PG8_BAR; PG8_MMA(1, 0, At, B0); PG8_MMA(1, 1, At, B1); PG8_BAR; PG8_SCHED;
.Ltl_qp_0d_p:
	s_waitcnt lgkmcnt(0)
	s_setprio 1
	s_barrier
	v_mfma_f32_16x16x32_bf16 v[126:129], v[10:13], v[146:149], 0
	v_mfma_f32_16x16x32_bf16 v[122:125], v[18:21], v[146:149], 0
	v_mfma_f32_16x16x32_bf16 v[110:113], v[10:13], v[162:165], 0
	v_mfma_f32_16x16x32_bf16 v[106:109], v[18:21], v[162:165], 0
	v_mfma_f32_16x16x32_bf16 v[94:97], v[10:13], v[178:181], 0
	v_mfma_f32_16x16x32_bf16 v[90:93], v[18:21], v[178:181], 0
	v_mfma_f32_16x16x32_bf16 v[10:13], v[10:13], v[198:201], 0
	v_mfma_f32_16x16x32_bf16 v[126:129], v[14:17], v[150:153], v[126:129]
	v_mfma_f32_16x16x32_bf16 v[122:125], v[22:25], v[150:153], v[122:125]
	v_mfma_f32_16x16x32_bf16 v[110:113], v[14:17], v[166:169], v[110:113]
	v_mfma_f32_16x16x32_bf16 v[106:109], v[22:25], v[166:169], v[106:109]
	v_mfma_f32_16x16x32_bf16 v[94:97], v[14:17], v[182:185], v[94:97]
	v_mfma_f32_16x16x32_bf16 v[90:93], v[22:25], v[182:185], v[90:93]
	v_mfma_f32_16x16x32_bf16 v[10:13], v[14:17], v[208:211], v[10:13]
	v_mfma_f32_16x16x32_bf16 v[14:17], v[18:21], v[198:201], 0
	v_mfma_f32_16x16x32_bf16 v[14:17], v[22:25], v[208:211], v[14:17]
	s_setprio 0
	s_setprio 1
	v_mfma_f32_16x16x32_bf16 v[74:77], v[26:29], v[162:165], 0
	v_mfma_f32_16x16x32_bf16 v[102:105], v[30:33], v[166:169], v[74:77]
	v_mfma_f32_16x16x32_bf16 v[74:77], v[42:45], v[162:165], 0
	v_mfma_f32_16x16x32_bf16 v[98:101], v[46:49], v[166:169], v[74:77]
	v_mfma_f32_16x16x32_bf16 v[74:77], v[26:29], v[178:181], 0
	v_mfma_f32_16x16x32_bf16 v[18:21], v[26:29], v[146:149], 0
	v_mfma_f32_16x16x32_bf16 v[86:89], v[30:33], v[182:185], v[74:77]
	v_mfma_f32_16x16x32_bf16 v[74:77], v[42:45], v[178:181], 0
	v_mfma_f32_16x16x32_bf16 v[26:29], v[26:29], v[198:201], 0
	v_mfma_f32_16x16x32_bf16 v[18:21], v[30:33], v[150:153], v[18:21]
	v_mfma_f32_16x16x32_bf16 v[22:25], v[42:45], v[146:149], 0
	v_mfma_f32_16x16x32_bf16 v[82:85], v[46:49], v[182:185], v[74:77]
	v_mfma_f32_16x16x32_bf16 v[26:29], v[30:33], v[208:211], v[26:29]
	v_mfma_f32_16x16x32_bf16 v[30:33], v[42:45], v[198:201], 0
	v_mfma_f32_16x16x32_bf16 v[22:25], v[46:49], v[150:153], v[22:25]
	v_mfma_f32_16x16x32_bf16 v[30:33], v[46:49], v[208:211], v[30:33]
	s_barrier
	s_branch .Lpeel_q_mid

; #define PG8_STAGE(bufoff, gbase, voff) do { _Pragma("unroll") for (int _i = 0; _i < 2; ++_i) \
;         __builtin_amdgcn_global_load_lds((const unsigned*)((const char*)(gbase) + (voff)[_i]), (LAS unsigned*)(lds + (bufoff) + ldsw + _i * 8192), 16, 0, 0); } while (0)
; #define PG8_LDA(dst, b, h) do { _Pragma("unroll") for (int m = 0; m < NM; ++m) _Pragma("unroll") for (int k = 0; k < 2; ++k) dst[m][k] = *(const LAS bf16x8*)(lds + PG8_SA(b, h) + aoff + m * 2048 + k * 1024); } while (0)
; #define PG8_LDB(dst, b, h) do { _Pragma("unroll") for (int n = 0; n < 2; ++n) _Pragma("unroll") for (int k = 0; k < 2; ++k) dst[n][k] = *(const LAS bf16x8*)(lds + PG8_SB(b, h) + boff + n * 2048 + k * 1024); } while (0)
; #define PG8_MMA(ai, bj, At, Bt) do { __builtin_amdgcn_s_setprio(1); _Pragma("unroll") for (int m = 0; m < NM; ++m) _Pragma("unroll") for (int n = 0; n < 2; ++n) _Pragma("unroll") for (int k = 0; k < 2; ++k) \
;         acc[ai][bj][m][n] = __builtin_amdgcn_mfma_f32_16x16x32_bf16(Bt[n][k], At[m][k], acc[ai][bj][m][n], 0, 0, 0); __builtin_amdgcn_s_setprio(0); } while (0)
; #define PG8_WAIT_V(n) asm volatile("s_waitcnt vmcnt(" #n ")" ::: "memory")
; #define PG8_WAIT_L(n) asm volatile("s_waitcnt lgkmcnt(" #n ")" ::: "memory")
; #define PG8_BAR __builtin_amdgcn_s_barrier()
; #define PG8_SCHED __builtin_amdgcn_sched_barrier(0)
;     ...
;             PG8_LDB(B0, 1, 0); PG8_LDB(B1, 1, 1); PG8_SCHED; PG8_LDA(At, 1, 0); PG8_STAGE(PG8_SA(0, 1), a2 + hstepA, voffA);
;             PG8_WAIT_V(8); PG8_WAIT_L(0); PG8_BAR; PG8_MMA(0, 0, At, B0); PG8_MMA(0, 1, At, B1); PG8_BAR; PG8_SCHED;
.Lpeel_q_mid:
	s_setprio 0
	v_add_u32_e32 v0, s69, v216
	ds_read_b128 v[42:45], v0
	ds_read_b128 v[46:49], v0 offset:1024
	ds_read_b128 v[66:69], v0 offset:2048
	ds_read_b128 v[70:73], v0 offset:3072
	v_add_u32_e32 v0, s74, v216
	ds_read_b128 v[178:181], v0
	ds_read_b128 v[182:185], v0 offset:1024
	ds_read_b128 v[198:201], v0 offset:2048
	ds_read_b128 v[208:211], v0 offset:3072
	s_add_u32 s34, s34, 0x20000
	s_addc_u32 s35, s35, 0
	s_mov_b32 m0, s64
	ds_read_b128 v[74:77], v217 offset:32768
	ds_read_b128 v[78:81], v217 offset:33792
	ds_read_b128 v[114:117], v217 offset:34816
	ds_read_b128 v[118:121], v217 offset:35840
	ds_read_b128 v[146:149], v217 offset:36864
	ds_read_b128 v[212:215], v217 offset:37888
	ds_read_b128 v[218:221], v217 offset:38912
	ds_read_b128 v[226:229], v217 offset:39936
	s_cmp_lg_u32 s100, 0
	s_cbranch_scc1 .Ltl_qp_1s
	global_load_lds_dwordx4 v186, s[34:35]
	s_mov_b32 m0, s68
	s_nop 0
	global_load_lds_dwordx4 v190, s[34:35]
	s_waitcnt vmcnt(8)
	s_branch .Ltl_qp_1d

;     __device__ __forceinline__ size_t aoff(const Unit& u) const { return (size_t)u.pm * bm * lda * 2; }
;     __device__ __forceinline__ size_t boff(const Unit& u) const { return (size_t)u.pn * BM * ldb * 2; }
;     __device__ __forceinline__ size_t aoff(const Unit& u) const { return ((size_t)u.pm * BM * lda + (size_t)u.pn * akoff) * 2; }
;     __device__ __forceinline__ size_t boff(const Unit& u) const { return (size_t)u.pn * BM * ldb * 2; }
;     __device__ __forceinline__ size_t aoff(const Unit& u) const { return ((size_t)u.pm * BM * lda + (size_t)(u.pn >> 1) * akoff) * 2; }
;     __device__ __forceinline__ size_t boff(const Unit& u) const { return (size_t)u.pn * BM * ldb * 2; }
; #define PG8_LDA(dst, b, h) do { _Pragma("unroll") for (int m = 0; m < NM; ++m) _Pragma("unroll") for (int k = 0; k < 2; ++k) dst[m][k] = *(const LAS bf16x8*)(lds + PG8_SA(b, h) + aoff + m * 2048 + k * 1024); } while (0)
;     ...
;         const bool has_next = S.next(ui + 1, nxt);
;         const char* nA = has_next ? (const char*)g.A + S.aoff(nxt) : cA; const char* nB = has_next ? (const char*)g.Bt + S.boff(nxt) : cB;
;         if constexpr (Epi::PRE) E.pre(lds, cur, wid);
;         for (int t = 0; t < nt; t += 2) {
;             const bool last = (t == nt - 2);
;             const char* a1 = cA + (size_t)(t + 1) * kstep;
;             const char* a2 = last ? nA : cA + (size_t)(t + 2) * kstep; const char* b2 = last ? nB : cB + (size_t)(t + 2) * kstep;
;             const char* a3 = a2 + kstep; const char* b3 = b2 + kstep;
;             if constexpr (SP2) {
;             PG8_LDB(B0, 0, 0); PG8_LDB(B1, 0, 1); PG8_SCHED; PG8_LDA(At, 0, 0); PG8_STAGE(PG8_SA(1, 1), a1 + hstepA, voffA);
;             PG8_WAIT_V(8); PG8_WAIT_L(0); PG8_BAR; PG8_MMA(0, 0, At, B0); PG8_MMA(0, 1, At, B1); PG8_BAR; PG8_SCHED;
;             PG8_LDA(At, 0, 1); PG8_STAGE(PG8_SB(0, 0), b2, voffB); PG8_STAGE(PG8_SB(0, 1), b2 + hstepB, voffB); PG8_STAGE(PG8_SA(0, 0), a2, voffA);
;             PG8_WAIT_V(8); PG8_WAIT_L(0); PG8_BAR; PG8_MMA(1, 0, At, B0); PG8_MMA(1, 1, At, B1); PG8_BAR; PG8_SCHED;
;     ...
; #pragma unroll
;         for (int a = 0; a < 2; ++a)
; #pragma unroll
;             for (int b = 0; b < 2; ++b)
; #pragma unroll
;                 for (int m = 0; m < NM; ++m)
; #pragma unroll
;                     for (int n = 0; n < 2; ++n) acc[a][b][m][n] = (f32x4){0.f, 0.f, 0.f, 0.f};
.LBB0_1453:
	s_ashr_i32 s15, s14, 31
	s_lshl_b64 s[2:3], s[14:15], 18
	s_add_u32 s18, s29, s2
	s_addc_u32 s19, s30, s3
	s_and_b64 s[2:3], s[6:7], exec
	s_cselect_b32 s2, s19, s23
	s_cselect_b32 s3, s18, s22
	s_add_u32 s15, s22, 0x100
	s_addc_u32 s60, s23, 0
	s_mov_b32 s73, -2
	v_add_u32_e32 v140, s31, v142
	ds_read_b128 v[144:147], v140
	ds_read_b128 v[148:151], v140 offset:1024
	ds_read_b128 v[152:155], v140 offset:2048
	ds_read_b128 v[156:159], v140 offset:3072
	v_add_u32_e32 v140, s35, v142
	ds_read_b128 v[160:163], v140
	ds_read_b128 v[164:167], v140 offset:1024
	ds_read_b128 v[168:171], v140 offset:2048
	ds_read_b128 v[172:175], v140 offset:3072
	s_add_u32 s6, s20, 0x100
	s_addc_u32 s7, s21, 0
	s_cmp_eq_u32 s73, 4
	s_cselect_b32 s25, s17, s7
	s_cselect_b32 s24, s16, s6
	s_cselect_b32 s23, s2, s60
	s_cselect_b32 s22, s3, s15
	s_cselect_b32 s100, -1, 0
	s_andn2_b32 s100, s100, s101
	s_add_i32 m0, s45, 0xc000
	ds_read_b128 v[176:179], v143
	ds_read_b128 v[180:183], v143 offset:1024
	ds_read_b128 v[184:187], v143 offset:2048
	ds_read_b128 v[188:191], v143 offset:3072
	ds_read_b128 v[192:195], v143 offset:4096
	ds_read_b128 v[196:199], v143 offset:5120
	ds_read_b128 v[200:203], v143 offset:6144
	ds_read_b128 v[208:211], v143 offset:7168
	global_load_lds_dwordx4 v136, s[20:21]
	s_add_i32 m0, s45, 0xe000
	s_nop 0
	global_load_lds_dwordx4 v138, s[20:21]
	s_waitcnt vmcnt(8)
	s_waitcnt lgkmcnt(0)
	s_setprio 1
	s_barrier
	v_mfma_f32_16x16x32_bf16 v[126:129], v[144:147], v[176:179], 0
	v_mfma_f32_16x16x32_bf16 v[122:125], v[152:155], v[176:179], 0
	v_mfma_f32_16x16x32_bf16 v[118:121], v[144:147], v[184:187], 0
	v_mfma_f32_16x16x32_bf16 v[114:117], v[152:155], v[184:187], 0
	v_mfma_f32_16x16x32_bf16 v[110:113], v[144:147], v[192:195], 0
	v_mfma_f32_16x16x32_bf16 v[106:109], v[152:155], v[192:195], 0
	v_mfma_f32_16x16x32_bf16 v[102:105], v[144:147], v[200:203], 0
	v_mfma_f32_16x16x32_bf16 v[98:101], v[152:155], v[200:203], 0
	v_mfma_f32_16x16x32_bf16 v[126:129], v[148:151], v[180:183], v[126:129]
	v_mfma_f32_16x16x32_bf16 v[122:125], v[156:159], v[180:183], v[122:125]
	v_mfma_f32_16x16x32_bf16 v[118:121], v[148:151], v[188:191], v[118:121]
	v_mfma_f32_16x16x32_bf16 v[114:117], v[156:159], v[188:191], v[114:117]
	v_mfma_f32_16x16x32_bf16 v[110:113], v[148:151], v[196:199], v[110:113]
	v_mfma_f32_16x16x32_bf16 v[106:109], v[156:159], v[196:199], v[106:109]
	v_mfma_f32_16x16x32_bf16 v[102:105], v[148:151], v[208:211], v[102:105]
	v_mfma_f32_16x16x32_bf16 v[98:101], v[156:159], v[208:211], v[98:101]
	s_setprio 0
	s_setprio 1
	v_mfma_f32_16x16x32_bf16 v[62:65], v[160:163], v[176:179], 0
	v_mfma_f32_16x16x32_bf16 v[58:61], v[168:171], v[176:179], 0
	v_mfma_f32_16x16x32_bf16 v[54:57], v[160:163], v[184:187], 0
	v_mfma_f32_16x16x32_bf16 v[50:53], v[168:171], v[184:187], 0
	v_mfma_f32_16x16x32_bf16 v[46:49], v[160:163], v[192:195], 0
	v_mfma_f32_16x16x32_bf16 v[42:45], v[168:171], v[192:195], 0
	v_mfma_f32_16x16x32_bf16 v[38:41], v[160:163], v[200:203], 0
	v_mfma_f32_16x16x32_bf16 v[34:37], v[168:171], v[200:203], 0
	v_mfma_f32_16x16x32_bf16 v[62:65], v[164:167], v[180:183], v[62:65]
	v_mfma_f32_16x16x32_bf16 v[58:61], v[172:175], v[180:183], v[58:61]
	v_mfma_f32_16x16x32_bf16 v[54:57], v[164:167], v[188:191], v[54:57]
	v_mfma_f32_16x16x32_bf16 v[50:53], v[172:175], v[188:191], v[50:53]
	v_mfma_f32_16x16x32_bf16 v[46:49], v[164:167], v[196:199], v[46:49]
	v_mfma_f32_16x16x32_bf16 v[42:45], v[172:175], v[196:199], v[42:45]
	v_mfma_f32_16x16x32_bf16 v[38:41], v[164:167], v[208:211], v[38:41]
	v_mfma_f32_16x16x32_bf16 v[34:37], v[172:175], v[208:211], v[34:37]
	s_barrier
	s_setprio 0
	s_mov_b32 m0, s33
	v_lshl_add_u64 v[140:141], s[22:23], 0, v[0:1]
	s_add_u32 s20, s22, 0x20000
	s_addc_u32 s21, s23, 0
	ds_read_b128 v[176:179], v143 offset:16384
	ds_read_b128 v[180:183], v143 offset:17408
	ds_read_b128 v[184:187], v143 offset:18432
	ds_read_b128 v[188:191], v143 offset:19456
	ds_read_b128 v[192:195], v143 offset:20480
	ds_read_b128 v[196:199], v143 offset:21504
	ds_read_b128 v[200:203], v143 offset:22528
	ds_read_b128 v[208:211], v143 offset:23552
	s_cmp_lg_u32 s100, 0
	s_cbranch_scc1 .Ltl_kv_0s_p
	global_load_lds_dwordx4 v0, s[22:23]
	v_lshl_add_u64 v[204:205], s[22:23], 0, v[134:135]
	s_mov_b32 m0, s34
	s_nop 0
	global_load_lds_dwordx4 v134, s[22:23]
	s_mov_b32 m0, s43
	v_lshl_add_u64 v[212:213], s[24:25], 0, v[132:133]
	global_load_lds_dwordx4 v0, s[20:21]
	s_mov_b32 m0, s44
	s_nop 0
	global_load_lds_dwordx4 v134, s[20:21]
	v_lshl_add_u64 v[206:207], s[24:25], 0, v[130:131]
	s_mov_b32 m0, s45
	s_nop 0
	global_load_lds_dwordx4 v130, s[24:25]
	s_mov_b32 m0, s47
	s_nop 0
	global_load_lds_dwordx4 v132, s[24:25]
	s_waitcnt vmcnt(8)
	s_branch .Ltl_kv_0d_p

; #define PG8_MMA(ai, bj, At, Bt) do { __builtin_amdgcn_s_setprio(1); _Pragma("unroll") for (int m = 0; m < NM; ++m) _Pragma("unroll") for (int n = 0; n < 2; ++n) _Pragma("unroll") for (int k = 0; k < 2; ++k) \
;         acc[ai][bj][m][n] = __builtin_amdgcn_mfma_f32_16x16x32_bf16(Bt[n][k], At[m][k], acc[ai][bj][m][n], 0, 0, 0); __builtin_amdgcn_s_setprio(0); } while (0)
; #define PG8_WAIT_V(n) asm volatile("s_waitcnt vmcnt(" #n ")" ::: "memory")
; #define PG8_WAIT_L(n) asm volatile("s_waitcnt lgkmcnt(" #n ")" ::: "memory")
; #define PG8_BAR __builtin_amdgcn_s_barrier()
; #define PG8_SCHED __builtin_amdgcn_sched_barrier(0)
;     ...
;             PG8_WAIT_V(8); PG8_WAIT_L(0); PG8_BAR; PG8_MMA(1, 0, At, B0); PG8_MMA(1, 1, At, B1); PG8_BAR; PG8_SCHED;
.Ltl_kv_0d_p:
	s_waitcnt lgkmcnt(0)
	s_setprio 1
	s_barrier
	v_mfma_f32_16x16x32_bf16 v[94:97], v[144:147], v[176:179], 0
	v_mfma_f32_16x16x32_bf16 v[90:93], v[152:155], v[176:179], 0
	v_mfma_f32_16x16x32_bf16 v[86:89], v[144:147], v[184:187], 0
	v_mfma_f32_16x16x32_bf16 v[82:85], v[152:155], v[184:187], 0
	v_mfma_f32_16x16x32_bf16 v[78:81], v[144:147], v[192:195], 0
	v_mfma_f32_16x16x32_bf16 v[74:77], v[152:155], v[192:195], 0
	v_mfma_f32_16x16x32_bf16 v[70:73], v[144:147], v[200:203], 0
	v_mfma_f32_16x16x32_bf16 v[66:69], v[152:155], v[200:203], 0
	v_mfma_f32_16x16x32_bf16 v[94:97], v[148:151], v[180:183], v[94:97]
	v_mfma_f32_16x16x32_bf16 v[90:93], v[156:159], v[180:183], v[90:93]
	v_mfma_f32_16x16x32_bf16 v[86:89], v[148:151], v[188:191], v[86:89]
	v_mfma_f32_16x16x32_bf16 v[82:85], v[156:159], v[188:191], v[82:85]
	v_mfma_f32_16x16x32_bf16 v[78:81], v[148:151], v[196:199], v[78:81]
	v_mfma_f32_16x16x32_bf16 v[74:77], v[156:159], v[196:199], v[74:77]
	v_mfma_f32_16x16x32_bf16 v[70:73], v[148:151], v[208:211], v[70:73]
	v_mfma_f32_16x16x32_bf16 v[66:69], v[156:159], v[208:211], v[66:69]
	s_setprio 0
	s_setprio 1
	v_mfma_f32_16x16x32_bf16 v[30:33], v[160:163], v[176:179], 0
	v_mfma_f32_16x16x32_bf16 v[26:29], v[168:171], v[176:179], 0
	v_mfma_f32_16x16x32_bf16 v[22:25], v[160:163], v[184:187], 0
	v_mfma_f32_16x16x32_bf16 v[18:21], v[168:171], v[184:187], 0
	v_mfma_f32_16x16x32_bf16 v[14:17], v[160:163], v[192:195], 0
	v_mfma_f32_16x16x32_bf16 v[10:13], v[168:171], v[192:195], 0
	v_mfma_f32_16x16x32_bf16 v[6:9], v[160:163], v[200:203], 0
	v_mfma_f32_16x16x32_bf16 v[2:5], v[168:171], v[200:203], 0
	v_mfma_f32_16x16x32_bf16 v[30:33], v[164:167], v[180:183], v[30:33]
	v_mfma_f32_16x16x32_bf16 v[26:29], v[172:175], v[180:183], v[26:29]
	v_mfma_f32_16x16x32_bf16 v[22:25], v[164:167], v[188:191], v[22:25]
	v_mfma_f32_16x16x32_bf16 v[18:21], v[172:175], v[188:191], v[18:21]
	v_mfma_f32_16x16x32_bf16 v[14:17], v[164:167], v[196:199], v[14:17]
	v_mfma_f32_16x16x32_bf16 v[10:13], v[172:175], v[196:199], v[10:13]
	v_mfma_f32_16x16x32_bf16 v[6:9], v[164:167], v[208:211], v[6:9]
	v_mfma_f32_16x16x32_bf16 v[2:5], v[172:175], v[208:211], v[2:5]
	s_barrier
	s_branch .Lpeel_kv_mid

; #define PG8_STAGE(bufoff, gbase, voff) do { _Pragma("unroll") for (int _i = 0; _i < 2; ++_i) \
;         __builtin_amdgcn_global_load_lds((const unsigned*)((const char*)(gbase) + (voff)[_i]), (LAS unsigned*)(lds + (bufoff) + ldsw + _i * 8192), 16, 0, 0); } while (0)
; #define PG8_LDA(dst, b, h) do { _Pragma("unroll") for (int m = 0; m < NM; ++m) _Pragma("unroll") for (int k = 0; k < 2; ++k) dst[m][k] = *(const LAS bf16x8*)(lds + PG8_SA(b, h) + aoff + m * 2048 + k * 1024); } while (0)
; #define PG8_LDB(dst, b, h) do { _Pragma("unroll") for (int n = 0; n < 2; ++n) _Pragma("unroll") for (int k = 0; k < 2; ++k) dst[n][k] = *(const LAS bf16x8*)(lds + PG8_SB(b, h) + boff + n * 2048 + k * 1024); } while (0)
; #define PG8_MMA(ai, bj, At, Bt) do { __builtin_amdgcn_s_setprio(1); _Pragma("unroll") for (int m = 0; m < NM; ++m) _Pragma("unroll") for (int n = 0; n < 2; ++n) _Pragma("unroll") for (int k = 0; k < 2; ++k) \
;         acc[ai][bj][m][n] = __builtin_amdgcn_mfma_f32_16x16x32_bf16(Bt[n][k], At[m][k], acc[ai][bj][m][n], 0, 0, 0); __builtin_amdgcn_s_setprio(0); } while (0)
; #define PG8_WAIT_V(n) asm volatile("s_waitcnt vmcnt(" #n ")" ::: "memory")
; #define PG8_WAIT_L(n) asm volatile("s_waitcnt lgkmcnt(" #n ")" ::: "memory")
; #define PG8_BAR __builtin_amdgcn_s_barrier()
; #define PG8_SCHED __builtin_amdgcn_sched_barrier(0)
;     ...
;             PG8_LDB(B0, 1, 0); PG8_LDB(B1, 1, 1); PG8_SCHED; PG8_LDA(At, 1, 0); PG8_STAGE(PG8_SA(0, 1), a2 + hstepA, voffA);
;             PG8_WAIT_V(8); PG8_WAIT_L(0); PG8_BAR; PG8_MMA(0, 0, At, B0); PG8_MMA(0, 1, At, B1); PG8_BAR; PG8_SCHED;
.Lpeel_kv_mid:
	s_setprio 0
	v_add_u32_e32 v156, s50, v142
	v_add_u32_e32 v172, s57, v142
	ds_read_b128 v[144:147], v156
	ds_read_b128 v[148:151], v156 offset:1024
	ds_read_b128 v[152:155], v156 offset:2048
	ds_read_b128 v[156:159], v156 offset:3072
	ds_read_b128 v[160:163], v172
	ds_read_b128 v[164:167], v172 offset:1024
	ds_read_b128 v[168:171], v172 offset:2048
	ds_read_b128 v[172:175], v172 offset:3072
	s_add_u32 s20, s24, 0x24000
	s_addc_u32 s21, s25, 0
	s_mov_b32 m0, s48
	ds_read_b128 v[176:179], v143 offset:32768
	ds_read_b128 v[180:183], v143 offset:33792
	ds_read_b128 v[184:187], v143 offset:34816
	ds_read_b128 v[188:191], v143 offset:35840
	ds_read_b128 v[192:195], v143 offset:36864
	ds_read_b128 v[196:199], v143 offset:37888
	ds_read_b128 v[200:203], v143 offset:38912
	ds_read_b128 v[208:211], v143 offset:39936
	s_cmp_lg_u32 s100, 0
	s_cbranch_scc1 .Ltl_kv_1s
	global_load_lds_dwordx4 v130, s[20:21]
	s_mov_b32 m0, s49
	s_nop 0
	global_load_lds_dwordx4 v132, s[20:21]
	s_waitcnt vmcnt(8)
	s_branch .Ltl_kv_1d

;     __device__ __forceinline__ size_t aoff(const Unit& u) const { return (size_t)u.pm * bm * lda * 2; }
;     __device__ __forceinline__ size_t boff(const Unit& u) const { return (size_t)u.pn * BM * ldb * 2; }
;     __device__ __forceinline__ size_t aoff(const Unit& u) const { return ((size_t)u.pm * BM * lda + (size_t)u.pn * akoff) * 2; }
;     __device__ __forceinline__ size_t boff(const Unit& u) const { return (size_t)u.pn * BM * ldb * 2; }
;     __device__ __forceinline__ size_t aoff(const Unit& u) const { return ((size_t)u.pm * BM * lda + (size_t)(u.pn >> 1) * akoff) * 2; }
;     __device__ __forceinline__ size_t boff(const Unit& u) const { return (size_t)u.pn * BM * ldb * 2; }
; #define PG8_STAGE(bufoff, gbase, voff) do { _Pragma("unroll") for (int _i = 0; _i < 2; ++_i) \
;         __builtin_amdgcn_global_load_lds((const unsigned*)((const char*)(gbase) + (voff)[_i]), (LAS unsigned*)(lds + (bufoff) + ldsw + _i * 8192), 16, 0, 0); } while (0)
; #define PG8_LDA(dst, b, h) do { _Pragma("unroll") for (int m = 0; m < NM; ++m) _Pragma("unroll") for (int k = 0; k < 2; ++k) dst[m][k] = *(const LAS bf16x8*)(lds + PG8_SA(b, h) + aoff + m * 2048 + k * 1024); } while (0)
; #define PG8_LDB(dst, b, h) do { _Pragma("unroll") for (int n = 0; n < 2; ++n) _Pragma("unroll") for (int k = 0; k < 2; ++k) dst[n][k] = *(const LAS bf16x8*)(lds + PG8_SB(b, h) + boff + n * 2048 + k * 1024); } while (0)
; #define PG8_WAIT_V(n) asm volatile("s_waitcnt vmcnt(" #n ")" ::: "memory")
;     ...
;         const bool has_next = S.next(ui + 1, nxt);
;         const char* nA = has_next ? (const char*)g.A + S.aoff(nxt) : cA; const char* nB = has_next ? (const char*)g.Bt + S.boff(nxt) : cB;
;         if constexpr (Epi::PRE) E.pre(lds, cur, wid);
;         for (int t = 0; t < nt; t += 2) {
;             const bool last = (t == nt - 2);
;             const char* a1 = cA + (size_t)(t + 1) * kstep;
;             const char* a2 = last ? nA : cA + (size_t)(t + 2) * kstep; const char* b2 = last ? nB : cB + (size_t)(t + 2) * kstep;
;             const char* a3 = a2 + kstep; const char* b3 = b2 + kstep;
;             if constexpr (SP2) {
;             PG8_LDB(B0, 0, 0); PG8_LDB(B1, 0, 1); PG8_SCHED; PG8_LDA(At, 0, 0); PG8_STAGE(PG8_SA(1, 1), a1 + hstepA, voffA);
;             PG8_WAIT_V(8); PG8_WAIT_L(0); PG8_BAR; PG8_MMA(0, 0, At, B0); PG8_MMA(0, 1, At, B1); PG8_BAR; PG8_SCHED;
.LBB0_1649:
	s_ashr_i32 s15, s14, 31
	s_lshl_b64 s[2:3], s[14:15], 20
	s_add_u32 s18, s5, s2
	s_addc_u32 s19, s26, s3
	s_and_b64 s[2:3], s[8:9], exec
	s_cselect_b32 s2, s19, s23
	s_cselect_b32 s3, s18, s22
	s_add_u32 s8, s24, 0x60080
	s_addc_u32 s9, s25, 0
	s_add_u32 s15, s22, 0x100
	s_addc_u32 s58, s23, 0
	s_mov_b32 s59, -2
	s_waitcnt vmcnt(5)
	v_add_u32_e32 v102, s21, v166
	v_add_u32_e32 v126, s31, v166
	ds_read_b128 v[90:93], v102
	ds_read_b128 v[94:97], v102 offset:1024
	ds_read_b128 v[98:101], v102 offset:2048
	ds_read_b128 v[102:105], v102 offset:3072
	ds_read_b128 v[114:117], v126
	ds_read_b128 v[118:121], v126 offset:1024
	ds_read_b128 v[122:125], v126 offset:2048
	ds_read_b128 v[126:129], v126 offset:3072
	s_add_u32 s22, s8, 0xfffa0080
	s_addc_u32 s23, s9, -1
	s_cmp_eq_u32 s59, 28
	s_cselect_b32 s25, s17, s23
	s_cselect_b32 s24, s16, s22
	s_cselect_b32 s23, s2, s58
	s_cselect_b32 s22, s3, s15
	s_cselect_b32 s100, -1, 0
	s_andn2_b32 s100, s100, s101
	s_add_i32 m0, s35, 0xc000
	ds_read_b128 v[130:133], v167
	ds_read_b128 v[134:137], v167 offset:1024
	ds_read_b128 v[138:141], v167 offset:2048
	ds_read_b128 v[152:155], v167 offset:3072
	ds_read_b128 v[156:159], v167 offset:4096
	ds_read_b128 v[160:163], v167 offset:5120
	global_load_lds_dwordx4 v148, s[8:9]
	s_add_i32 m0, s35, 0xe000
	s_nop 0
	s_and_b64 vcc, exec, s[10:11]
	s_cbranch_vccz .Lnm3o_skip0_p
	global_load_lds_dwordx4 v150, s[8:9]
	s_waitcnt vmcnt(8)
	s_branch .Lnm3o_done0_p

; #define PG8_STAGE(bufoff, gbase, voff) do { _Pragma("unroll") for (int _i = 0; _i < 2; ++_i) \
;         __builtin_amdgcn_global_load_lds((const unsigned*)((const char*)(gbase) + (voff)[_i]), (LAS unsigned*)(lds + (bufoff) + ldsw + _i * 8192), 16, 0, 0); } while (0)
; #define PG8_LDA(dst, b, h) do { _Pragma("unroll") for (int m = 0; m < NM; ++m) _Pragma("unroll") for (int k = 0; k < 2; ++k) dst[m][k] = *(const LAS bf16x8*)(lds + PG8_SA(b, h) + aoff + m * 2048 + k * 1024); } while (0)
; #define PG8_MMA(ai, bj, At, Bt) do { __builtin_amdgcn_s_setprio(1); _Pragma("unroll") for (int m = 0; m < NM; ++m) _Pragma("unroll") for (int n = 0; n < 2; ++n) _Pragma("unroll") for (int k = 0; k < 2; ++k) \
;         acc[ai][bj][m][n] = __builtin_amdgcn_mfma_f32_16x16x32_bf16(Bt[n][k], At[m][k], acc[ai][bj][m][n], 0, 0, 0); __builtin_amdgcn_s_setprio(0); } while (0)
; #define PG8_WAIT_V(n) asm volatile("s_waitcnt vmcnt(" #n ")" ::: "memory")
; #define PG8_WAIT_L(n) asm volatile("s_waitcnt lgkmcnt(" #n ")" ::: "memory")
; #define PG8_BAR __builtin_amdgcn_s_barrier()
; #define PG8_SCHED __builtin_amdgcn_sched_barrier(0)
;     ...
;             PG8_WAIT_V(8); PG8_WAIT_L(0); PG8_BAR; PG8_MMA(0, 0, At, B0); PG8_MMA(0, 1, At, B1); PG8_BAR; PG8_SCHED;
;             PG8_LDA(At, 0, 1); PG8_STAGE(PG8_SB(0, 0), b2, voffB); PG8_STAGE(PG8_SB(0, 1), b2 + hstepB, voffB); PG8_STAGE(PG8_SA(0, 0), a2, voffA);
.Lnm3o_done0_p:
	s_waitcnt lgkmcnt(0)
	s_setprio 1
	s_barrier
	v_mfma_f32_16x16x32_bf16 v[110:113], v[90:93], v[130:133], 0
	v_mfma_f32_16x16x32_bf16 v[106:109], v[98:101], v[130:133], 0
	v_mfma_f32_16x16x32_bf16 v[78:81], v[90:93], v[138:141], 0
	v_mfma_f32_16x16x32_bf16 v[74:77], v[98:101], v[138:141], 0
	v_mfma_f32_16x16x32_bf16 v[62:65], v[90:93], v[156:159], 0
	v_mfma_f32_16x16x32_bf16 v[58:61], v[98:101], v[156:159], 0
	v_mfma_f32_16x16x32_bf16 v[110:113], v[94:97], v[134:137], v[110:113]
	v_mfma_f32_16x16x32_bf16 v[106:109], v[102:105], v[134:137], v[106:109]
	v_mfma_f32_16x16x32_bf16 v[78:81], v[94:97], v[152:155], v[78:81]
	v_mfma_f32_16x16x32_bf16 v[74:77], v[102:105], v[152:155], v[74:77]
	v_mfma_f32_16x16x32_bf16 v[62:65], v[94:97], v[160:163], v[62:65]
	v_mfma_f32_16x16x32_bf16 v[58:61], v[102:105], v[160:163], v[58:61]
	s_setprio 0
	s_setprio 1
	v_mfma_f32_16x16x32_bf16 v[86:89], v[114:117], v[130:133], 0
	v_mfma_f32_16x16x32_bf16 v[82:85], v[122:125], v[130:133], 0
	v_mfma_f32_16x16x32_bf16 v[70:73], v[114:117], v[138:141], 0
	v_mfma_f32_16x16x32_bf16 v[66:69], v[122:125], v[138:141], 0
	v_mfma_f32_16x16x32_bf16 v[54:57], v[114:117], v[156:159], 0
	v_mfma_f32_16x16x32_bf16 v[50:53], v[122:125], v[156:159], 0
	v_mfma_f32_16x16x32_bf16 v[86:89], v[118:121], v[134:137], v[86:89]
	v_mfma_f32_16x16x32_bf16 v[82:85], v[126:129], v[134:137], v[82:85]
	v_mfma_f32_16x16x32_bf16 v[70:73], v[118:121], v[152:155], v[70:73]
	v_mfma_f32_16x16x32_bf16 v[66:69], v[126:129], v[152:155], v[66:69]
	v_mfma_f32_16x16x32_bf16 v[54:57], v[118:121], v[160:163], v[54:57]
	v_mfma_f32_16x16x32_bf16 v[50:53], v[126:129], v[160:163], v[50:53]
	s_barrier
	s_setprio 0
	s_mov_b32 m0, s29
	v_lshl_add_u64 v[164:165], s[22:23], 0, v[0:1]
	s_add_u32 s62, s22, 0x80000
	s_addc_u32 s63, s23, 0
	ds_read_b128 v[130:133], v167 offset:16384
	ds_read_b128 v[134:137], v167 offset:17408
	ds_read_b128 v[138:141], v167 offset:18432
	ds_read_b128 v[152:155], v167 offset:19456
	ds_read_b128 v[156:159], v167 offset:20480
	ds_read_b128 v[160:163], v167 offset:21504
	s_cmp_lg_u32 s100, 0
	s_cbranch_scc1 .Ltl_ou_0s_p
	global_load_lds_dwordx4 v0, s[22:23]
	v_lshl_add_u64 v[168:169], s[22:23], 0, v[146:147]
	s_mov_b32 m0, s30
	s_nop 0
	global_load_lds_dwordx4 v146, s[22:23]
	s_mov_b32 m0, s33
	v_lshl_add_u64 v[172:173], s[24:25], 0, v[144:145]
	global_load_lds_dwordx4 v0, s[62:63]
	s_mov_b32 m0, s34
	s_nop 0
	global_load_lds_dwordx4 v146, s[62:63]
	v_lshl_add_u64 v[170:171], s[24:25], 0, v[142:143]
	s_mov_b32 m0, s35
	s_nop 0
	global_load_lds_dwordx4 v142, s[24:25]
	s_mov_b32 m0, s36
	s_nop 0
	s_and_b64 vcc, exec, s[10:11]
	s_cbranch_vccz .Lnm3o_skip1_p
	global_load_lds_dwordx4 v144, s[24:25]
	s_waitcnt vmcnt(8)
	s_branch .Lnm3o_done1_p

; #define PG8_MMA(ai, bj, At, Bt) do { __builtin_amdgcn_s_setprio(1); _Pragma("unroll") for (int m = 0; m < NM; ++m) _Pragma("unroll") for (int n = 0; n < 2; ++n) _Pragma("unroll") for (int k = 0; k < 2; ++k) \
;         acc[ai][bj][m][n] = __builtin_amdgcn_mfma_f32_16x16x32_bf16(Bt[n][k], At[m][k], acc[ai][bj][m][n], 0, 0, 0); __builtin_amdgcn_s_setprio(0); } while (0)
; #define PG8_WAIT_V(n) asm volatile("s_waitcnt vmcnt(" #n ")" ::: "memory")
; #define PG8_WAIT_L(n) asm volatile("s_waitcnt lgkmcnt(" #n ")" ::: "memory")
; #define PG8_BAR __builtin_amdgcn_s_barrier()
; #define PG8_SCHED __builtin_amdgcn_sched_barrier(0)
;     ...
;             PG8_WAIT_V(8); PG8_WAIT_L(0); PG8_BAR; PG8_MMA(1, 0, At, B0); PG8_MMA(1, 1, At, B1); PG8_BAR; PG8_SCHED;
.Ltl_ou_0d_p:
	s_waitcnt lgkmcnt(0)
	s_setprio 1
	s_barrier
	v_mfma_f32_16x16x32_bf16 v[46:49], v[90:93], v[130:133], 0
	v_mfma_f32_16x16x32_bf16 v[42:45], v[98:101], v[130:133], 0
	v_mfma_f32_16x16x32_bf16 v[30:33], v[90:93], v[138:141], 0
	v_mfma_f32_16x16x32_bf16 v[26:29], v[98:101], v[138:141], 0
	v_mfma_f32_16x16x32_bf16 v[14:17], v[90:93], v[156:159], 0
	v_mfma_f32_16x16x32_bf16 v[10:13], v[98:101], v[156:159], 0
	v_mfma_f32_16x16x32_bf16 v[46:49], v[94:97], v[134:137], v[46:49]
	v_mfma_f32_16x16x32_bf16 v[42:45], v[102:105], v[134:137], v[42:45]
	v_mfma_f32_16x16x32_bf16 v[30:33], v[94:97], v[152:155], v[30:33]
	v_mfma_f32_16x16x32_bf16 v[26:29], v[102:105], v[152:155], v[26:29]
	v_mfma_f32_16x16x32_bf16 v[14:17], v[94:97], v[160:163], v[14:17]
	v_mfma_f32_16x16x32_bf16 v[10:13], v[102:105], v[160:163], v[10:13]
	s_setprio 0
	s_setprio 1
	v_mfma_f32_16x16x32_bf16 v[38:41], v[114:117], v[130:133], 0
	v_mfma_f32_16x16x32_bf16 v[34:37], v[122:125], v[130:133], 0
	v_mfma_f32_16x16x32_bf16 v[22:25], v[114:117], v[138:141], 0
	v_mfma_f32_16x16x32_bf16 v[18:21], v[122:125], v[138:141], 0
	v_mfma_f32_16x16x32_bf16 v[6:9], v[114:117], v[156:159], 0
	v_mfma_f32_16x16x32_bf16 v[2:5], v[122:125], v[156:159], 0
	v_mfma_f32_16x16x32_bf16 v[38:41], v[118:121], v[134:137], v[38:41]
	v_mfma_f32_16x16x32_bf16 v[34:37], v[126:129], v[134:137], v[34:37]
	v_mfma_f32_16x16x32_bf16 v[22:25], v[118:121], v[152:155], v[22:25]
	v_mfma_f32_16x16x32_bf16 v[18:21], v[126:129], v[152:155], v[18:21]
	v_mfma_f32_16x16x32_bf16 v[6:9], v[118:121], v[160:163], v[6:9]
	v_mfma_f32_16x16x32_bf16 v[2:5], v[126:129], v[160:163], v[2:5]
	s_barrier
	s_branch .Lpeel_op_mid

; #define PG8_STAGE(bufoff, gbase, voff) do { _Pragma("unroll") for (int _i = 0; _i < 2; ++_i) \
;         __builtin_amdgcn_global_load_lds((const unsigned*)((const char*)(gbase) + (voff)[_i]), (LAS unsigned*)(lds + (bufoff) + ldsw + _i * 8192), 16, 0, 0); } while (0)
; #define PG8_LDA(dst, b, h) do { _Pragma("unroll") for (int m = 0; m < NM; ++m) _Pragma("unroll") for (int k = 0; k < 2; ++k) dst[m][k] = *(const LAS bf16x8*)(lds + PG8_SA(b, h) + aoff + m * 2048 + k * 1024); } while (0)
; #define PG8_LDB(dst, b, h) do { _Pragma("unroll") for (int n = 0; n < 2; ++n) _Pragma("unroll") for (int k = 0; k < 2; ++k) dst[n][k] = *(const LAS bf16x8*)(lds + PG8_SB(b, h) + boff + n * 2048 + k * 1024); } while (0)
; #define PG8_MMA(ai, bj, At, Bt) do { __builtin_amdgcn_s_setprio(1); _Pragma("unroll") for (int m = 0; m < NM; ++m) _Pragma("unroll") for (int n = 0; n < 2; ++n) _Pragma("unroll") for (int k = 0; k < 2; ++k) \
;         acc[ai][bj][m][n] = __builtin_amdgcn_mfma_f32_16x16x32_bf16(Bt[n][k], At[m][k], acc[ai][bj][m][n], 0, 0, 0); __builtin_amdgcn_s_setprio(0); } while (0)
; #define PG8_WAIT_V(n) asm volatile("s_waitcnt vmcnt(" #n ")" ::: "memory")
; #define PG8_WAIT_L(n) asm volatile("s_waitcnt lgkmcnt(" #n ")" ::: "memory")
; #define PG8_BAR __builtin_amdgcn_s_barrier()
; #define PG8_SCHED __builtin_amdgcn_sched_barrier(0)
;     ...
;             PG8_LDB(B0, 1, 0); PG8_LDB(B1, 1, 1); PG8_SCHED; PG8_LDA(At, 1, 0); PG8_STAGE(PG8_SA(0, 1), a2 + hstepA, voffA);
;             PG8_WAIT_V(8); PG8_WAIT_L(0); PG8_BAR; PG8_MMA(0, 0, At, B0); PG8_MMA(0, 1, At, B1); PG8_BAR; PG8_SCHED;
.Lpeel_op_mid:
	s_setprio 0
	v_add_u32_e32 v102, s40, v166
	v_add_u32_e32 v126, s45, v166
	ds_read_b128 v[90:93], v102
	ds_read_b128 v[94:97], v102 offset:1024
	ds_read_b128 v[98:101], v102 offset:2048
	ds_read_b128 v[102:105], v102 offset:3072
	ds_read_b128 v[114:117], v126
	ds_read_b128 v[118:121], v126 offset:1024
	ds_read_b128 v[122:125], v126 offset:2048
	ds_read_b128 v[126:129], v126 offset:3072
	s_add_u32 s24, s24, 0x60000
	s_addc_u32 s25, s25, 0
	s_mov_b32 m0, s37
	ds_read_b128 v[130:133], v167 offset:32768
	ds_read_b128 v[134:137], v167 offset:33792
	ds_read_b128 v[138:141], v167 offset:34816
	ds_read_b128 v[152:155], v167 offset:35840
	ds_read_b128 v[156:159], v167 offset:36864
	ds_read_b128 v[160:163], v167 offset:37888
	s_cmp_lg_u32 s100, 0
	s_cbranch_scc1 .Ltl_ou_1s
	global_load_lds_dwordx4 v142, s[24:25]
	s_mov_b32 m0, s38
	s_nop 0
	s_and_b64 vcc, exec, s[10:11]
	s_cbranch_vccz .Lnm3o_skip2
	global_load_lds_dwordx4 v144, s[24:25]
	s_waitcnt vmcnt(8)
	s_branch .Lnm3o_done2

;     __device__ __forceinline__ size_t aoff(const Unit& u) const { return (size_t)u.pm * bm * lda * 2; }
;     __device__ __forceinline__ size_t boff(const Unit& u) const { return (size_t)u.pn * BM * ldb * 2; }
;     __device__ __forceinline__ size_t aoff(const Unit& u) const { return ((size_t)u.pm * BM * lda + (size_t)u.pn * akoff) * 2; }
;     __device__ __forceinline__ size_t boff(const Unit& u) const { return (size_t)u.pn * BM * ldb * 2; }
;     __device__ __forceinline__ size_t aoff(const Unit& u) const { return ((size_t)u.pm * BM * lda + (size_t)(u.pn >> 1) * akoff) * 2; }
;     __device__ __forceinline__ size_t boff(const Unit& u) const { return (size_t)u.pn * BM * ldb * 2; }
; #define PG8_LDA(dst, b, h) do { _Pragma("unroll") for (int m = 0; m < NM; ++m) _Pragma("unroll") for (int k = 0; k < 2; ++k) dst[m][k] = *(const LAS bf16x8*)(lds + PG8_SA(b, h) + aoff + m * 2048 + k * 1024); } while (0)
;     ...
;         const bool has_next = S.next(ui + 1, nxt);
;         const char* nA = has_next ? (const char*)g.A + S.aoff(nxt) : cA; const char* nB = has_next ? (const char*)g.Bt + S.boff(nxt) : cB;
;         if constexpr (Epi::PRE) E.pre(lds, cur, wid);
;         for (int t = 0; t < nt; t += 2) {
;             const bool last = (t == nt - 2);
;             const char* a1 = cA + (size_t)(t + 1) * kstep;
;             const char* a2 = last ? nA : cA + (size_t)(t + 2) * kstep; const char* b2 = last ? nB : cB + (size_t)(t + 2) * kstep;
;             const char* a3 = a2 + kstep; const char* b3 = b2 + kstep;
;             if constexpr (SP2) {
;             PG8_LDB(B0, 0, 0); PG8_LDB(B1, 0, 1); PG8_SCHED; PG8_LDA(At, 0, 0); PG8_STAGE(PG8_SA(1, 1), a1 + hstepA, voffA);
;             PG8_WAIT_V(8); PG8_WAIT_L(0); PG8_BAR; PG8_MMA(0, 0, At, B0); PG8_MMA(0, 1, At, B1); PG8_BAR; PG8_SCHED;
;             PG8_LDA(At, 0, 1); PG8_STAGE(PG8_SB(0, 0), b2, voffB); PG8_STAGE(PG8_SB(0, 1), b2 + hstepB, voffB); PG8_STAGE(PG8_SA(0, 0), a2, voffA);
;             PG8_WAIT_V(8); PG8_WAIT_L(0); PG8_BAR; PG8_MMA(1, 0, At, B0); PG8_MMA(1, 1, At, B1); PG8_BAR; PG8_SCHED;
;     ...
; #pragma unroll
;         for (int a = 0; a < 2; ++a)
; #pragma unroll
;             for (int b = 0; b < 2; ++b)
; #pragma unroll
;                 for (int m = 0; m < NM; ++m)
; #pragma unroll
;                     for (int n = 0; n < 2; ++n) acc[a][b][m][n] = (f32x4){0.f, 0.f, 0.f, 0.f};
.LBB0_1782:
	s_ashr_i32 s41, s40, 31
	s_lshl_b64 s[2:3], s[40:41], 20
	s_add_u32 s42, s33, s2
	s_addc_u32 s43, s48, s3
	s_and_b64 s[2:3], s[6:7], exec
	s_cselect_b32 s2, s43, s13
	s_cselect_b32 s3, s42, s12
	s_ashr_i32 s37, s36, 31
	s_lshl_b64 s[44:45], s[36:37], 20
	s_add_u32 s44, s60, s44
	s_addc_u32 s45, s63, s45
	s_and_b64 s[46:47], s[6:7], exec
	s_cselect_b32 s9, s45, s15
	s_cselect_b32 s11, s44, s14
	s_add_u32 s12, s12, 0x80080
	s_addc_u32 s13, s13, 0
	s_add_u32 s37, s14, 0x100
	s_addc_u32 s41, s15, 0
	s_mov_b32 vcc_lo, -2
	s_waitcnt vmcnt(5)
	v_add_u32_e32 v0, s64, v208
	ds_read_b128 v[130:133], v0
	ds_read_b128 v[134:137], v0 offset:1024
	ds_read_b128 v[138:141], v0 offset:2048
	ds_read_b128 v[142:145], v0 offset:3072
	v_add_u32_e32 v0, s70, v208
	ds_read_b128 v[146:149], v0
	ds_read_b128 v[150:153], v0 offset:1024
	ds_read_b128 v[154:157], v0 offset:2048
	ds_read_b128 v[158:161], v0 offset:3072
	s_add_u32 s14, s12, 0xfff80080
	s_addc_u32 s15, s13, -1
	s_cmp_eq_u32 vcc_lo, 28
	s_cselect_b32 s47, s2, s15
	s_cselect_b32 s46, s3, s14
	s_cselect_b32 s15, s9, s41
	s_cselect_b32 s14, s11, s37
	s_cselect_b32 s100, -1, 0
	s_andn2_b32 s100, s100, s101
	s_add_i32 m0, s73, 0xc000
	ds_read_b128 v[162:165], v209
	ds_read_b128 v[166:169], v209 offset:1024
	ds_read_b128 v[170:173], v209 offset:2048
	ds_read_b128 v[174:177], v209 offset:3072
	ds_read_b128 v[190:193], v209 offset:4096
	ds_read_b128 v[194:197], v209 offset:5120
	ds_read_b128 v[198:201], v209 offset:6144
	ds_read_b128 v[202:205], v209 offset:7168
	global_load_lds_dwordx4 v186, s[12:13]
	s_add_i32 m0, s73, 0xe000
	s_nop 0
	global_load_lds_dwordx4 v188, s[12:13]
	s_waitcnt vmcnt(8)
	s_waitcnt lgkmcnt(0)
	s_setprio 1
	s_barrier
	v_mfma_f32_16x16x32_bf16 v[126:129], v[130:133], v[162:165], 0
	v_mfma_f32_16x16x32_bf16 v[94:97], v[138:141], v[162:165], 0
	v_mfma_f32_16x16x32_bf16 v[110:113], v[130:133], v[170:173], 0
	v_mfma_f32_16x16x32_bf16 v[70:73], v[138:141], v[170:173], 0
	v_mfma_f32_16x16x32_bf16 v[106:109], v[130:133], v[190:193], 0
	v_mfma_f32_16x16x32_bf16 v[66:69], v[138:141], v[190:193], 0
	v_mfma_f32_16x16x32_bf16 v[118:121], v[130:133], v[198:201], 0
	v_mfma_f32_16x16x32_bf16 v[86:89], v[138:141], v[198:201], 0
	v_mfma_f32_16x16x32_bf16 v[126:129], v[134:137], v[166:169], v[126:129]
	v_mfma_f32_16x16x32_bf16 v[94:97], v[142:145], v[166:169], v[94:97]
	v_mfma_f32_16x16x32_bf16 v[110:113], v[134:137], v[174:177], v[110:113]
	v_mfma_f32_16x16x32_bf16 v[70:73], v[142:145], v[174:177], v[70:73]
	v_mfma_f32_16x16x32_bf16 v[106:109], v[134:137], v[194:197], v[106:109]
	v_mfma_f32_16x16x32_bf16 v[66:69], v[142:145], v[194:197], v[66:69]
	v_mfma_f32_16x16x32_bf16 v[118:121], v[134:137], v[202:205], v[118:121]
	v_mfma_f32_16x16x32_bf16 v[86:89], v[142:145], v[202:205], v[86:89]
	s_setprio 0
	s_setprio 1
	v_mfma_f32_16x16x32_bf16 v[122:125], v[146:149], v[162:165], 0
	v_mfma_f32_16x16x32_bf16 v[90:93], v[154:157], v[162:165], 0
	v_mfma_f32_16x16x32_bf16 v[102:105], v[146:149], v[170:173], 0
	v_mfma_f32_16x16x32_bf16 v[62:65], v[154:157], v[170:173], 0
	v_mfma_f32_16x16x32_bf16 v[98:101], v[146:149], v[190:193], 0
	v_mfma_f32_16x16x32_bf16 v[58:61], v[154:157], v[190:193], 0
	v_mfma_f32_16x16x32_bf16 v[114:117], v[146:149], v[198:201], 0
	v_mfma_f32_16x16x32_bf16 v[82:85], v[154:157], v[198:201], 0
	v_mfma_f32_16x16x32_bf16 v[122:125], v[150:153], v[166:169], v[122:125]
	v_mfma_f32_16x16x32_bf16 v[90:93], v[158:161], v[166:169], v[90:93]
	v_mfma_f32_16x16x32_bf16 v[102:105], v[150:153], v[174:177], v[102:105]
	v_mfma_f32_16x16x32_bf16 v[62:65], v[158:161], v[174:177], v[62:65]
	v_mfma_f32_16x16x32_bf16 v[98:101], v[150:153], v[194:197], v[98:101]
	v_mfma_f32_16x16x32_bf16 v[58:61], v[158:161], v[194:197], v[58:61]
	v_mfma_f32_16x16x32_bf16 v[114:117], v[150:153], v[202:205], v[114:117]
	v_mfma_f32_16x16x32_bf16 v[82:85], v[158:161], v[202:205], v[82:85]
	s_barrier
	s_setprio 0
	s_mov_b32 m0, s68
	s_add_u32 s22, s14, 0x80000
	s_addc_u32 s23, s15, 0
	ds_read_b128 v[162:165], v209 offset:16384
	ds_read_b128 v[166:169], v209 offset:17408
	ds_read_b128 v[170:173], v209 offset:18432
	ds_read_b128 v[174:177], v209 offset:19456
	ds_read_b128 v[190:193], v209 offset:20480
	ds_read_b128 v[194:197], v209 offset:21504
	ds_read_b128 v[198:201], v209 offset:22528
	ds_read_b128 v[202:205], v209 offset:23552
	s_cmp_lg_u32 s100, 0
	s_cbranch_scc1 .Ltl_up_0s_p
	global_load_lds_dwordx4 v180, s[14:15]
	s_mov_b32 m0, s69
	s_nop 0
	global_load_lds_dwordx4 v184, s[14:15]
	s_mov_b32 m0, s71
	s_nop 0
	global_load_lds_dwordx4 v180, s[22:23]
	s_mov_b32 m0, s72
	s_nop 0
	global_load_lds_dwordx4 v184, s[22:23]
	s_mov_b32 m0, s73
	s_nop 0
	global_load_lds_dwordx4 v178, s[46:47]
	s_mov_b32 m0, s74
	s_nop 0
	global_load_lds_dwordx4 v182, s[46:47]
	s_waitcnt vmcnt(8)
	s_branch .Ltl_up_0d_p

; #define PG8_MMA(ai, bj, At, Bt) do { __builtin_amdgcn_s_setprio(1); _Pragma("unroll") for (int m = 0; m < NM; ++m) _Pragma("unroll") for (int n = 0; n < 2; ++n) _Pragma("unroll") for (int k = 0; k < 2; ++k) \
;         acc[ai][bj][m][n] = __builtin_amdgcn_mfma_f32_16x16x32_bf16(Bt[n][k], At[m][k], acc[ai][bj][m][n], 0, 0, 0); __builtin_amdgcn_s_setprio(0); } while (0)
; #define PG8_WAIT_V(n) asm volatile("s_waitcnt vmcnt(" #n ")" ::: "memory")
; #define PG8_WAIT_L(n) asm volatile("s_waitcnt lgkmcnt(" #n ")" ::: "memory")
; #define PG8_BAR __builtin_amdgcn_s_barrier()
; #define PG8_SCHED __builtin_amdgcn_sched_barrier(0)
;     ...
;             PG8_WAIT_V(8); PG8_WAIT_L(0); PG8_BAR; PG8_MMA(1, 0, At, B0); PG8_MMA(1, 1, At, B1); PG8_BAR; PG8_SCHED;
.Ltl_up_0d_p:
	s_waitcnt lgkmcnt(0)
	s_setprio 1
	s_barrier
	v_mfma_f32_16x16x32_bf16 v[46:49], v[130:133], v[162:165], 0
	v_mfma_f32_16x16x32_bf16 v[22:25], v[138:141], v[162:165], 0
	v_mfma_f32_16x16x32_bf16 v[42:45], v[130:133], v[170:173], 0
	v_mfma_f32_16x16x32_bf16 v[18:21], v[138:141], v[170:173], 0
	v_mfma_f32_16x16x32_bf16 v[38:41], v[130:133], v[190:193], 0
	v_mfma_f32_16x16x32_bf16 v[14:17], v[138:141], v[190:193], 0
	v_mfma_f32_16x16x32_bf16 v[78:81], v[130:133], v[198:201], 0
	v_mfma_f32_16x16x32_bf16 v[54:57], v[138:141], v[198:201], 0
	v_mfma_f32_16x16x32_bf16 v[46:49], v[134:137], v[166:169], v[46:49]
	v_mfma_f32_16x16x32_bf16 v[22:25], v[142:145], v[166:169], v[22:25]
	v_mfma_f32_16x16x32_bf16 v[42:45], v[134:137], v[174:177], v[42:45]
	v_mfma_f32_16x16x32_bf16 v[18:21], v[142:145], v[174:177], v[18:21]
	v_mfma_f32_16x16x32_bf16 v[38:41], v[134:137], v[194:197], v[38:41]
	v_mfma_f32_16x16x32_bf16 v[14:17], v[142:145], v[194:197], v[14:17]
	v_mfma_f32_16x16x32_bf16 v[78:81], v[134:137], v[202:205], v[78:81]
	v_mfma_f32_16x16x32_bf16 v[54:57], v[142:145], v[202:205], v[54:57]
	s_setprio 0
	s_setprio 1
	v_mfma_f32_16x16x32_bf16 v[34:37], v[146:149], v[162:165], 0
	v_mfma_f32_16x16x32_bf16 v[10:13], v[154:157], v[162:165], 0
	v_mfma_f32_16x16x32_bf16 v[30:33], v[146:149], v[170:173], 0
	v_mfma_f32_16x16x32_bf16 v[6:9], v[154:157], v[170:173], 0
	v_mfma_f32_16x16x32_bf16 v[26:29], v[146:149], v[190:193], 0
	v_mfma_f32_16x16x32_bf16 v[2:5], v[154:157], v[190:193], 0
	v_mfma_f32_16x16x32_bf16 v[74:77], v[146:149], v[198:201], 0
	v_mfma_f32_16x16x32_bf16 v[50:53], v[154:157], v[198:201], 0
	v_mfma_f32_16x16x32_bf16 v[34:37], v[150:153], v[166:169], v[34:37]
	v_mfma_f32_16x16x32_bf16 v[10:13], v[158:161], v[166:169], v[10:13]
	v_mfma_f32_16x16x32_bf16 v[30:33], v[150:153], v[174:177], v[30:33]
	v_mfma_f32_16x16x32_bf16 v[6:9], v[158:161], v[174:177], v[6:9]
	v_mfma_f32_16x16x32_bf16 v[26:29], v[150:153], v[194:197], v[26:29]
	v_mfma_f32_16x16x32_bf16 v[2:5], v[158:161], v[194:197], v[2:5]
	v_mfma_f32_16x16x32_bf16 v[74:77], v[150:153], v[202:205], v[74:77]
	v_mfma_f32_16x16x32_bf16 v[50:53], v[158:161], v[202:205], v[50:53]
	s_barrier
	s_branch .Lpeel_up_mid

; #define PG8_STAGE(bufoff, gbase, voff) do { _Pragma("unroll") for (int _i = 0; _i < 2; ++_i) \
;         __builtin_amdgcn_global_load_lds((const unsigned*)((const char*)(gbase) + (voff)[_i]), (LAS unsigned*)(lds + (bufoff) + ldsw + _i * 8192), 16, 0, 0); } while (0)
; #define PG8_LDA(dst, b, h) do { _Pragma("unroll") for (int m = 0; m < NM; ++m) _Pragma("unroll") for (int k = 0; k < 2; ++k) dst[m][k] = *(const LAS bf16x8*)(lds + PG8_SA(b, h) + aoff + m * 2048 + k * 1024); } while (0)
; #define PG8_LDB(dst, b, h) do { _Pragma("unroll") for (int n = 0; n < 2; ++n) _Pragma("unroll") for (int k = 0; k < 2; ++k) dst[n][k] = *(const LAS bf16x8*)(lds + PG8_SB(b, h) + boff + n * 2048 + k * 1024); } while (0)
; #define PG8_MMA(ai, bj, At, Bt) do { __builtin_amdgcn_s_setprio(1); _Pragma("unroll") for (int m = 0; m < NM; ++m) _Pragma("unroll") for (int n = 0; n < 2; ++n) _Pragma("unroll") for (int k = 0; k < 2; ++k) \
;         acc[ai][bj][m][n] = __builtin_amdgcn_mfma_f32_16x16x32_bf16(Bt[n][k], At[m][k], acc[ai][bj][m][n], 0, 0, 0); __builtin_amdgcn_s_setprio(0); } while (0)
; #define PG8_WAIT_V(n) asm volatile("s_waitcnt vmcnt(" #n ")" ::: "memory")
; #define PG8_WAIT_L(n) asm volatile("s_waitcnt lgkmcnt(" #n ")" ::: "memory")
; #define PG8_BAR __builtin_amdgcn_s_barrier()
; #define PG8_SCHED __builtin_amdgcn_sched_barrier(0)
;     ...
;             PG8_LDB(B0, 1, 0); PG8_LDB(B1, 1, 1); PG8_SCHED; PG8_LDA(At, 1, 0); PG8_STAGE(PG8_SA(0, 1), a2 + hstepA, voffA);
;             PG8_WAIT_V(8); PG8_WAIT_L(0); PG8_BAR; PG8_MMA(0, 0, At, B0); PG8_MMA(0, 1, At, B1); PG8_BAR; PG8_SCHED;
.Lpeel_up_mid:
	s_setprio 0
	v_add_u32_e32 v0, s94, v208
	ds_read_b128 v[130:133], v0
	ds_read_b128 v[134:137], v0 offset:1024
	ds_read_b128 v[138:141], v0 offset:2048
	ds_read_b128 v[142:145], v0 offset:3072
	v_add_u32_e32 v0, s62, v208
	ds_read_b128 v[146:149], v0
	ds_read_b128 v[150:153], v0 offset:1024
	ds_read_b128 v[154:157], v0 offset:2048
	ds_read_b128 v[158:161], v0 offset:3072
	s_add_u32 s22, s46, 0x80000
	s_addc_u32 s23, s47, 0
	s_mov_b32 m0, s75
	ds_read_b128 v[162:165], v209 offset:32768
	ds_read_b128 v[166:169], v209 offset:33792
	ds_read_b128 v[170:173], v209 offset:34816
	ds_read_b128 v[174:177], v209 offset:35840
	ds_read_b128 v[190:193], v209 offset:36864
	ds_read_b128 v[194:197], v209 offset:37888
	ds_read_b128 v[198:201], v209 offset:38912
	ds_read_b128 v[202:205], v209 offset:39936
	s_cmp_lg_u32 s100, 0
	s_cbranch_scc1 .Ltl_up_1s
	global_load_lds_dwordx4 v178, s[22:23]
	s_mov_b32 m0, s80
	s_nop 0
	global_load_lds_dwordx4 v182, s[22:23]
	s_waitcnt vmcnt(8)
	s_branch .Ltl_up_1d

;     __device__ __forceinline__ size_t aoff(const Unit& u) const { return (size_t)u.pm * bm * lda * 2; }
;     __device__ __forceinline__ size_t boff(const Unit& u) const { return (size_t)u.pn * BM * ldb * 2; }
;     __device__ __forceinline__ size_t aoff(const Unit& u) const { return ((size_t)u.pm * BM * lda + (size_t)u.pn * akoff) * 2; }
;     __device__ __forceinline__ size_t boff(const Unit& u) const { return (size_t)u.pn * BM * ldb * 2; }
;     __device__ __forceinline__ size_t aoff(const Unit& u) const { return ((size_t)u.pm * BM * lda + (size_t)(u.pn >> 1) * akoff) * 2; }
;     __device__ __forceinline__ size_t boff(const Unit& u) const { return (size_t)u.pn * BM * ldb * 2; }
; #define PG8_STAGE(bufoff, gbase, voff) do { _Pragma("unroll") for (int _i = 0; _i < 2; ++_i) \
;         __builtin_amdgcn_global_load_lds((const unsigned*)((const char*)(gbase) + (voff)[_i]), (LAS unsigned*)(lds + (bufoff) + ldsw + _i * 8192), 16, 0, 0); } while (0)
; #define PG8_LDA(dst, b, h) do { _Pragma("unroll") for (int m = 0; m < NM; ++m) _Pragma("unroll") for (int k = 0; k < 2; ++k) dst[m][k] = *(const LAS bf16x8*)(lds + PG8_SA(b, h) + aoff + m * 2048 + k * 1024); } while (0)
; #define PG8_LDB(dst, b, h) do { _Pragma("unroll") for (int n = 0; n < 2; ++n) _Pragma("unroll") for (int k = 0; k < 2; ++k) dst[n][k] = *(const LAS bf16x8*)(lds + PG8_SB(b, h) + boff + n * 2048 + k * 1024); } while (0)
; #define PG8_WAIT_V(n) asm volatile("s_waitcnt vmcnt(" #n ")" ::: "memory")
;     ...
;         const bool has_next = S.next(ui + 1, nxt);
;         const char* nA = has_next ? (const char*)g.A + S.aoff(nxt) : cA; const char* nB = has_next ? (const char*)g.Bt + S.boff(nxt) : cB;
;         if constexpr (Epi::PRE) E.pre(lds, cur, wid);
;         for (int t = 0; t < nt; t += 2) {
;             const bool last = (t == nt - 2);
;             const char* a1 = cA + (size_t)(t + 1) * kstep;
;             const char* a2 = last ? nA : cA + (size_t)(t + 2) * kstep; const char* b2 = last ? nB : cB + (size_t)(t + 2) * kstep;
;             const char* a3 = a2 + kstep; const char* b3 = b2 + kstep;
;             if constexpr (SP2) {
;             PG8_LDB(B0, 0, 0); PG8_LDB(B1, 0, 1); PG8_SCHED; PG8_LDA(At, 0, 0); PG8_STAGE(PG8_SA(1, 1), a1 + hstepA, voffA);
;             PG8_WAIT_V(8); PG8_WAIT_L(0); PG8_BAR; PG8_MMA(0, 0, At, B0); PG8_MMA(0, 1, At, B1); PG8_BAR; PG8_SCHED;
.LBB0_2157:
	s_add_u32 s2, s16, 0x100
	s_addc_u32 s3, s17, 0
	s_mov_b32 s60, -2
	s_waitcnt vmcnt(5)
	v_add_u32_e32 v102, s26, v166
	v_add_u32_e32 v126, s29, v166
	ds_read_b128 v[90:93], v102
	ds_read_b128 v[94:97], v102 offset:1024
	ds_read_b128 v[98:101], v102 offset:2048
	ds_read_b128 v[102:105], v102 offset:3072
	ds_read_b128 v[114:117], v126
	ds_read_b128 v[118:121], v126 offset:1024
	ds_read_b128 v[122:125], v126 offset:2048
	ds_read_b128 v[126:129], v126 offset:3072
	s_add_u32 s16, s14, 0x100
	s_addc_u32 s17, s15, 0
	s_cmpk_eq_i32 s60, 0x54
	s_cselect_b32 s21, s7, s17
	s_cselect_b32 s20, s6, s16
	s_cselect_b32 s19, s13, s3
	s_cselect_b32 s18, s12, s2
	s_cselect_b32 s100, -1, 0
	s_andn2_b32 s100, s100, s101
	s_add_i32 m0, s34, 0xc000
	ds_read_b128 v[130:133], v167
	ds_read_b128 v[134:137], v167 offset:1024
	ds_read_b128 v[138:141], v167 offset:2048
	ds_read_b128 v[152:155], v167 offset:3072
	ds_read_b128 v[156:159], v167 offset:4096
	ds_read_b128 v[160:163], v167 offset:5120
	global_load_lds_dwordx4 v148, s[14:15]
	s_add_i32 m0, s34, 0xe000
	s_nop 0
	s_and_b64 vcc, exec, s[8:9]
	s_cbranch_vccz .Lnm3d_skip0_p
	global_load_lds_dwordx4 v150, s[14:15]
	s_waitcnt vmcnt(8)
	s_branch .Lnm3d_done0_p

; #define PG8_STAGE(bufoff, gbase, voff) do { _Pragma("unroll") for (int _i = 0; _i < 2; ++_i) \
;         __builtin_amdgcn_global_load_lds((const unsigned*)((const char*)(gbase) + (voff)[_i]), (LAS unsigned*)(lds + (bufoff) + ldsw + _i * 8192), 16, 0, 0); } while (0)
; #define PG8_LDA(dst, b, h) do { _Pragma("unroll") for (int m = 0; m < NM; ++m) _Pragma("unroll") for (int k = 0; k < 2; ++k) dst[m][k] = *(const LAS bf16x8*)(lds + PG8_SA(b, h) + aoff + m * 2048 + k * 1024); } while (0)
; #define PG8_MMA(ai, bj, At, Bt) do { __builtin_amdgcn_s_setprio(1); _Pragma("unroll") for (int m = 0; m < NM; ++m) _Pragma("unroll") for (int n = 0; n < 2; ++n) _Pragma("unroll") for (int k = 0; k < 2; ++k) \
;         acc[ai][bj][m][n] = __builtin_amdgcn_mfma_f32_16x16x32_bf16(Bt[n][k], At[m][k], acc[ai][bj][m][n], 0, 0, 0); __builtin_amdgcn_s_setprio(0); } while (0)
; #define PG8_WAIT_V(n) asm volatile("s_waitcnt vmcnt(" #n ")" ::: "memory")
; #define PG8_WAIT_L(n) asm volatile("s_waitcnt lgkmcnt(" #n ")" ::: "memory")
; #define PG8_BAR __builtin_amdgcn_s_barrier()
; #define PG8_SCHED __builtin_amdgcn_sched_barrier(0)
;     ...
;             PG8_WAIT_V(8); PG8_WAIT_L(0); PG8_BAR; PG8_MMA(0, 0, At, B0); PG8_MMA(0, 1, At, B1); PG8_BAR; PG8_SCHED;
;             PG8_LDA(At, 0, 1); PG8_STAGE(PG8_SB(0, 0), b2, voffB); PG8_STAGE(PG8_SB(0, 1), b2 + hstepB, voffB); PG8_STAGE(PG8_SA(0, 0), a2, voffA);
.Lnm3d_done0_p:
	s_waitcnt lgkmcnt(0)
	s_setprio 1
	s_barrier
	v_mfma_f32_16x16x32_bf16 v[110:113], v[90:93], v[130:133], 0
	v_mfma_f32_16x16x32_bf16 v[106:109], v[98:101], v[130:133], 0
	v_mfma_f32_16x16x32_bf16 v[78:81], v[90:93], v[138:141], 0
	v_mfma_f32_16x16x32_bf16 v[74:77], v[98:101], v[138:141], 0
	v_mfma_f32_16x16x32_bf16 v[62:65], v[90:93], v[156:159], 0
	v_mfma_f32_16x16x32_bf16 v[58:61], v[98:101], v[156:159], 0
	v_mfma_f32_16x16x32_bf16 v[110:113], v[94:97], v[134:137], v[110:113]
	v_mfma_f32_16x16x32_bf16 v[106:109], v[102:105], v[134:137], v[106:109]
	v_mfma_f32_16x16x32_bf16 v[78:81], v[94:97], v[152:155], v[78:81]
	v_mfma_f32_16x16x32_bf16 v[74:77], v[102:105], v[152:155], v[74:77]
	v_mfma_f32_16x16x32_bf16 v[62:65], v[94:97], v[160:163], v[62:65]
	v_mfma_f32_16x16x32_bf16 v[58:61], v[102:105], v[160:163], v[58:61]
	s_setprio 0
	s_setprio 1
	v_mfma_f32_16x16x32_bf16 v[86:89], v[114:117], v[130:133], 0
	v_mfma_f32_16x16x32_bf16 v[82:85], v[122:125], v[130:133], 0
	v_mfma_f32_16x16x32_bf16 v[70:73], v[114:117], v[138:141], 0
	v_mfma_f32_16x16x32_bf16 v[66:69], v[122:125], v[138:141], 0
	v_mfma_f32_16x16x32_bf16 v[54:57], v[114:117], v[156:159], 0
	v_mfma_f32_16x16x32_bf16 v[50:53], v[122:125], v[156:159], 0
	v_mfma_f32_16x16x32_bf16 v[86:89], v[118:121], v[134:137], v[86:89]
	v_mfma_f32_16x16x32_bf16 v[82:85], v[126:129], v[134:137], v[82:85]
	v_mfma_f32_16x16x32_bf16 v[70:73], v[118:121], v[152:155], v[70:73]
	v_mfma_f32_16x16x32_bf16 v[66:69], v[126:129], v[152:155], v[66:69]
	v_mfma_f32_16x16x32_bf16 v[54:57], v[118:121], v[160:163], v[54:57]
	v_mfma_f32_16x16x32_bf16 v[50:53], v[126:129], v[160:163], v[50:53]
	s_barrier
	s_setprio 0
	s_mov_b32 m0, s27
	v_lshl_add_u64 v[164:165], s[18:19], 0, v[0:1]
	s_add_u32 s14, s18, 0x160000
	s_addc_u32 s15, s19, 0
	ds_read_b128 v[130:133], v167 offset:16384
	ds_read_b128 v[134:137], v167 offset:17408
	ds_read_b128 v[138:141], v167 offset:18432
	ds_read_b128 v[152:155], v167 offset:19456
	ds_read_b128 v[156:159], v167 offset:20480
	ds_read_b128 v[160:163], v167 offset:21504
	s_cmp_lg_u32 s100, 0
	s_cbranch_scc1 .Ltl_dn_0s_p
	global_load_lds_dwordx4 v0, s[18:19]
	v_lshl_add_u64 v[168:169], s[18:19], 0, v[146:147]
	s_mov_b32 m0, s28
	s_nop 0
	global_load_lds_dwordx4 v146, s[18:19]
	s_mov_b32 m0, s30
	v_lshl_add_u64 v[172:173], s[20:21], 0, v[144:145]
	global_load_lds_dwordx4 v0, s[14:15]
	s_mov_b32 m0, s31
	s_nop 0
	global_load_lds_dwordx4 v146, s[14:15]
	v_lshl_add_u64 v[170:171], s[20:21], 0, v[142:143]
	s_mov_b32 m0, s34
	s_nop 0
	global_load_lds_dwordx4 v142, s[20:21]
	s_mov_b32 m0, s35
	s_nop 0
	s_and_b64 vcc, exec, s[8:9]
	s_cbranch_vccz .Lnm3d_skip1_p
	global_load_lds_dwordx4 v144, s[20:21]
	s_waitcnt vmcnt(8)
	s_branch .Lnm3d_done1_p

; #define PG8_STAGE(bufoff, gbase, voff) do { _Pragma("unroll") for (int _i = 0; _i < 2; ++_i) \
;         __builtin_amdgcn_global_load_lds((const unsigned*)((const char*)(gbase) + (voff)[_i]), (LAS unsigned*)(lds + (bufoff) + ldsw + _i * 8192), 16, 0, 0); } while (0)
; #define PG8_LDA(dst, b, h) do { _Pragma("unroll") for (int m = 0; m < NM; ++m) _Pragma("unroll") for (int k = 0; k < 2; ++k) dst[m][k] = *(const LAS bf16x8*)(lds + PG8_SA(b, h) + aoff + m * 2048 + k * 1024); } while (0)
; #define PG8_LDB(dst, b, h) do { _Pragma("unroll") for (int n = 0; n < 2; ++n) _Pragma("unroll") for (int k = 0; k < 2; ++k) dst[n][k] = *(const LAS bf16x8*)(lds + PG8_SB(b, h) + boff + n * 2048 + k * 1024); } while (0)
; #define PG8_MMA(ai, bj, At, Bt) do { __builtin_amdgcn_s_setprio(1); _Pragma("unroll") for (int m = 0; m < NM; ++m) _Pragma("unroll") for (int n = 0; n < 2; ++n) _Pragma("unroll") for (int k = 0; k < 2; ++k) \
;         acc[ai][bj][m][n] = __builtin_amdgcn_mfma_f32_16x16x32_bf16(Bt[n][k], At[m][k], acc[ai][bj][m][n], 0, 0, 0); __builtin_amdgcn_s_setprio(0); } while (0)
; #define PG8_WAIT_V(n) asm volatile("s_waitcnt vmcnt(" #n ")" ::: "memory")
; #define PG8_WAIT_L(n) asm volatile("s_waitcnt lgkmcnt(" #n ")" ::: "memory")
; #define PG8_BAR __builtin_amdgcn_s_barrier()
; #define PG8_SCHED __builtin_amdgcn_sched_barrier(0)
;     ...
;             PG8_LDB(B0, 1, 0); PG8_LDB(B1, 1, 1); PG8_SCHED; PG8_LDA(At, 1, 0); PG8_STAGE(PG8_SA(0, 1), a2 + hstepA, voffA);
;             PG8_WAIT_V(8); PG8_WAIT_L(0); PG8_BAR; PG8_MMA(0, 0, At, B0); PG8_MMA(0, 1, At, B1); PG8_BAR; PG8_SCHED;
.Lpeel_dn_mid:
	s_setprio 0
	v_add_u32_e32 v102, s38, v166
	v_add_u32_e32 v126, s45, v166
	ds_read_b128 v[90:93], v102
	ds_read_b128 v[94:97], v102 offset:1024
	ds_read_b128 v[98:101], v102 offset:2048
	ds_read_b128 v[102:105], v102 offset:3072
	ds_read_b128 v[114:117], v126
	ds_read_b128 v[118:121], v126 offset:1024
	ds_read_b128 v[122:125], v126 offset:2048
	ds_read_b128 v[126:129], v126 offset:3072
	s_add_u32 s14, s20, 0x108000
	s_addc_u32 s15, s21, 0
	s_mov_b32 m0, s36
	ds_read_b128 v[130:133], v167 offset:32768
	ds_read_b128 v[134:137], v167 offset:33792
	ds_read_b128 v[138:141], v167 offset:34816
	ds_read_b128 v[152:155], v167 offset:35840
	ds_read_b128 v[156:159], v167 offset:36864
	ds_read_b128 v[160:163], v167 offset:37888
	s_cmp_lg_u32 s100, 0
	s_cbranch_scc1 .Ltl_dn_1s
	global_load_lds_dwordx4 v142, s[14:15]
	s_mov_b32 m0, s37
	s_nop 0
	s_and_b64 vcc, exec, s[8:9]
	s_cbranch_vccz .Lnm3d_skip2
	global_load_lds_dwordx4 v144, s[14:15]
	s_waitcnt vmcnt(8)
	s_branch .Lnm3d_done2
